# phase-5 epilogue: inlined expm1f (27 instr) replaced by 1 - exp2(y*log2e) in f32 (stored as fp16 as before)
# speedup vs baseline: 1.0204x; 1.0023x over previous
; __device__ __forceinline__ float sigmoidf_(float x) { return 1.0f / (1.0f + __expf(-x)); }
;     __device__ __forceinline__ void operator()(const f32x4 (&acc)[2][2][4][2], const Unit& u, int wr, int wc, int fr, int fq) const {
;     ...
;                         for (int i = 0; i < 4; ++i) { float xv = acc[ai][bj][m][n][i] + bv[bj][n][i]; float r;
;                             if (type < 2) { const float sg = sigmoidf_(xv); r = -expm1f(-0.606531f * sg); }
;                             else if (type == 2) r = sigmoidf_(xv);
;                             else r = xv;
;                             v[4 * n + i] = (f16)r; }
.LBB0_473:
	v_mul_f32_e32 v140, 0xbfb8aa3b, v140
	v_exp_f32_e32 v140, v140
	s_nop 0
	v_add_f32_e32 v140, 1.0, v140
	v_rcp_f32_e32 v162, v140
	s_nop 0
	v_fma_f32 v174, -v140, v162, 1.0
	v_fma_f32 v152, v174, v162, v162
	v_div_fixup_f32 v140, v152, v140, 1.0
	v_mul_f32_e32 v140, 0xbf1b459e, v140
	v_mul_f32_e32 v152, 0x3fb8aa3b, v140
	v_exp_f32_e32 v152, v152
	s_nop 0
	v_sub_f32_e32 v152, 1.0, v152

; __device__ __forceinline__ float sigmoidf_(float x) { return 1.0f / (1.0f + __expf(-x)); }
;     __device__ __forceinline__ void operator()(const f32x4 (&acc)[2][2][4][2], const Unit& u, int wr, int wc, int fr, int fq) const {
;     ...
;                         for (int i = 0; i < 4; ++i) { float xv = acc[ai][bj][m][n][i] + bv[bj][n][i]; float r;
;                             if (type < 2) { const float sg = sigmoidf_(xv); r = -expm1f(-0.606531f * sg); }
;                             else if (type == 2) r = sigmoidf_(xv);
;                             else r = xv;
;                             v[4 * n + i] = (f16)r; }
.LBB0_479:
	v_mul_f32_e32 v140, 0xbfb8aa3b, v140
	v_exp_f32_e32 v140, v140
	s_nop 0
	v_add_f32_e32 v140, 1.0, v140
	v_rcp_f32_e32 v162, v140
	s_nop 0
	v_fma_f32 v174, -v140, v162, 1.0
	v_fma_f32 v141, v174, v162, v162
	v_div_fixup_f32 v140, v141, v140, 1.0
	v_mul_f32_e32 v140, 0xbf1b459e, v140
	v_mul_f32_e32 v141, 0x3fb8aa3b, v140
	v_exp_f32_e32 v141, v141
	s_nop 0
	v_sub_f32_e32 v162, 1.0, v141

; __device__ __forceinline__ float sigmoidf_(float x) { return 1.0f / (1.0f + __expf(-x)); }
;     __device__ __forceinline__ void operator()(const f32x4 (&acc)[2][2][4][2], const Unit& u, int wr, int wc, int fr, int fq) const {
;     ...
;                         for (int i = 0; i < 4; ++i) { float xv = acc[ai][bj][m][n][i] + bv[bj][n][i]; float r;
;                             if (type < 2) { const float sg = sigmoidf_(xv); r = -expm1f(-0.606531f * sg); }
;                             else if (type == 2) r = sigmoidf_(xv);
;                             else r = xv;
;                             v[4 * n + i] = (f16)r; }
.LBB0_485:
	v_mul_f32_e32 v140, 0xbfb8aa3b, v140
	v_exp_f32_e32 v140, v140
	s_nop 0
	v_add_f32_e32 v140, 1.0, v140
	v_rcp_f32_e32 v142, v140
	s_nop 0
	v_fma_f32 v174, -v140, v142, 1.0
	v_fma_f32 v141, v174, v142, v142
	v_div_fixup_f32 v140, v141, v140, 1.0
	v_mul_f32_e32 v140, 0xbf1b459e, v140
	v_mul_f32_e32 v141, 0x3fb8aa3b, v140
	v_exp_f32_e32 v141, v141
	s_nop 0
	v_sub_f32_e32 v142, 1.0, v141

; __device__ __forceinline__ float sigmoidf_(float x) { return 1.0f / (1.0f + __expf(-x)); }
;     __device__ __forceinline__ void operator()(const f32x4 (&acc)[2][2][4][2], const Unit& u, int wr, int wc, int fr, int fq) const {
;     ...
;                         for (int i = 0; i < 4; ++i) { float xv = acc[ai][bj][m][n][i] + bv[bj][n][i]; float r;
;                             if (type < 2) { const float sg = sigmoidf_(xv); r = -expm1f(-0.606531f * sg); }
;                             else if (type == 2) r = sigmoidf_(xv);
;                             else r = xv;
;                             v[4 * n + i] = (f16)r; }
.LBB0_491:
	v_mul_f32_e32 v140, 0xbfb8aa3b, v140
	v_exp_f32_e32 v140, v140
	s_nop 0
	v_add_f32_e32 v140, 1.0, v140
	v_rcp_f32_e32 v143, v140
	s_nop 0
	v_fma_f32 v174, -v140, v143, 1.0
	v_fma_f32 v141, v174, v143, v143
	v_div_fixup_f32 v140, v141, v140, 1.0
	v_mul_f32_e32 v140, 0xbf1b459e, v140
	v_mul_f32_e32 v141, 0x3fb8aa3b, v140
	v_exp_f32_e32 v141, v141
	s_nop 0
	v_sub_f32_e32 v143, 1.0, v141

; __device__ __forceinline__ float sigmoidf_(float x) { return 1.0f / (1.0f + __expf(-x)); }
;     __device__ __forceinline__ void operator()(const f32x4 (&acc)[2][2][4][2], const Unit& u, int wr, int wc, int fr, int fq) const {
;     ...
;                         for (int i = 0; i < 4; ++i) { float xv = acc[ai][bj][m][n][i] + bv[bj][n][i]; float r;
;                             if (type < 2) { const float sg = sigmoidf_(xv); r = -expm1f(-0.606531f * sg); }
;                             else if (type == 2) r = sigmoidf_(xv);
;                             else r = xv;
;                             v[4 * n + i] = (f16)r; }
.LBB0_497:
	v_mul_f32_e32 v136, 0xbfb8aa3b, v136
	v_exp_f32_e32 v136, v136
	s_nop 0
	v_add_f32_e32 v136, 1.0, v136
	v_rcp_f32_e32 v141, v136
	s_nop 0
	v_fma_f32 v174, -v136, v141, 1.0
	v_fma_f32 v140, v174, v141, v141
	v_div_fixup_f32 v136, v140, v136, 1.0
	v_mul_f32_e32 v136, 0xbf1b459e, v136
	v_mul_f32_e32 v140, 0x3fb8aa3b, v136
	v_exp_f32_e32 v140, v140
	s_nop 0
	v_sub_f32_e32 v163, 1.0, v140

; __device__ __forceinline__ float sigmoidf_(float x) { return 1.0f / (1.0f + __expf(-x)); }
;     __device__ __forceinline__ void operator()(const f32x4 (&acc)[2][2][4][2], const Unit& u, int wr, int wc, int fr, int fq) const {
;     ...
;                         for (int i = 0; i < 4; ++i) { float xv = acc[ai][bj][m][n][i] + bv[bj][n][i]; float r;
;                             if (type < 2) { const float sg = sigmoidf_(xv); r = -expm1f(-0.606531f * sg); }
;                             else if (type == 2) r = sigmoidf_(xv);
;                             else r = xv;
;                             v[4 * n + i] = (f16)r; }
.LBB0_503:
	v_mul_f32_e32 v136, 0xbfb8aa3b, v136
	v_exp_f32_e32 v136, v136
	s_nop 0
	v_add_f32_e32 v136, 1.0, v136
	v_rcp_f32_e32 v140, v136
	s_nop 0
	v_fma_f32 v174, -v136, v140, 1.0
	v_fma_f32 v137, v174, v140, v140
	v_div_fixup_f32 v136, v137, v136, 1.0
	v_mul_f32_e32 v136, 0xbf1b459e, v136
	v_mul_f32_e32 v137, 0x3fb8aa3b, v136
	v_exp_f32_e32 v137, v137
	s_nop 0
	v_sub_f32_e32 v174, 1.0, v137

; __device__ __forceinline__ float sigmoidf_(float x) { return 1.0f / (1.0f + __expf(-x)); }
;     __device__ __forceinline__ void operator()(const f32x4 (&acc)[2][2][4][2], const Unit& u, int wr, int wc, int fr, int fq) const {
;     ...
;                         for (int i = 0; i < 4; ++i) { float xv = acc[ai][bj][m][n][i] + bv[bj][n][i]; float r;
;                             if (type < 2) { const float sg = sigmoidf_(xv); r = -expm1f(-0.606531f * sg); }
;                             else if (type == 2) r = sigmoidf_(xv);
;                             else r = xv;
;                             v[4 * n + i] = (f16)r; }
.LBB0_509:
	v_mul_f32_e32 v136, 0xbfb8aa3b, v136
	v_exp_f32_e32 v136, v136
	s_nop 0
	v_add_f32_e32 v136, 1.0, v136
	v_rcp_f32_e32 v138, v136
	s_nop 0
	v_fma_f32 v141, -v136, v138, 1.0
	v_fma_f32 v137, v141, v138, v138
	v_div_fixup_f32 v136, v137, v136, 1.0
	v_mul_f32_e32 v136, 0xbf1b459e, v136
	v_mul_f32_e32 v137, 0x3fb8aa3b, v136
	v_exp_f32_e32 v137, v137
	s_nop 0
	v_sub_f32_e32 v175, 1.0, v137

; __device__ __forceinline__ float sigmoidf_(float x) { return 1.0f / (1.0f + __expf(-x)); }
;     __device__ __forceinline__ void operator()(const f32x4 (&acc)[2][2][4][2], const Unit& u, int wr, int wc, int fr, int fq) const {
;     ...
;                         for (int i = 0; i < 4; ++i) { float xv = acc[ai][bj][m][n][i] + bv[bj][n][i]; float r;
;                             if (type < 2) { const float sg = sigmoidf_(xv); r = -expm1f(-0.606531f * sg); }
;                             else if (type == 2) r = sigmoidf_(xv);
;                             else r = xv;
;                             v[4 * n + i] = (f16)r; }
.LBB0_515:
	v_mul_f32_e32 v136, 0xbfb8aa3b, v136
	v_exp_f32_e32 v136, v136
	s_nop 0
	v_add_f32_e32 v136, 1.0, v136
	v_rcp_f32_e32 v138, v136
	s_nop 0
	v_fma_f32 v140, -v136, v138, 1.0
	v_fma_f32 v137, v140, v138, v138
	v_div_fixup_f32 v136, v137, v136, 1.0
	v_mul_f32_e32 v136, 0xbf1b459e, v136
	v_mul_f32_e32 v137, 0x3fb8aa3b, v136
	v_exp_f32_e32 v137, v137
	s_nop 0
	v_sub_f32_e32 v176, 1.0, v137

; __device__ __forceinline__ float sigmoidf_(float x) { return 1.0f / (1.0f + __expf(-x)); }
;     __device__ __forceinline__ void operator()(const f32x4 (&acc)[2][2][4][2], const Unit& u, int wr, int wc, int fr, int fq) const {
;     ...
;                         for (int i = 0; i < 4; ++i) { float xv = acc[ai][bj][m][n][i] + bv[bj][n][i]; float r;
;                             if (type < 2) { const float sg = sigmoidf_(xv); r = -expm1f(-0.606531f * sg); }
;                             else if (type == 2) r = sigmoidf_(xv);
;                             else r = xv;
;                             v[4 * n + i] = (f16)r; }
.LBB0_521:
	v_mul_f32_e32 v132, 0xbfb8aa3b, v142
	v_exp_f32_e32 v132, v132
	s_nop 0
	v_add_f32_e32 v132, 1.0, v132
	v_rcp_f32_e32 v143, v132
	s_nop 0
	v_fma_f32 v162, -v132, v143, 1.0
	v_fma_f32 v142, v162, v143, v143
	v_div_fixup_f32 v132, v142, v132, 1.0
	v_mul_f32_e32 v132, 0xbf1b459e, v132
	v_mul_f32_e32 v142, 0x3fb8aa3b, v132
	v_exp_f32_e32 v142, v142
	s_nop 0
	v_sub_f32_e32 v132, 1.0, v142

; __device__ __forceinline__ float sigmoidf_(float x) { return 1.0f / (1.0f + __expf(-x)); }
;     __device__ __forceinline__ void operator()(const f32x4 (&acc)[2][2][4][2], const Unit& u, int wr, int wc, int fr, int fq) const {
;     ...
;                         for (int i = 0; i < 4; ++i) { float xv = acc[ai][bj][m][n][i] + bv[bj][n][i]; float r;
;                             if (type < 2) { const float sg = sigmoidf_(xv); r = -expm1f(-0.606531f * sg); }
;                             else if (type == 2) r = sigmoidf_(xv);
;                             else r = xv;
;                             v[4 * n + i] = (f16)r; }
.LBB0_527:
	v_mul_f32_e32 v133, 0xbfb8aa3b, v142
	v_exp_f32_e32 v133, v133
	s_nop 0
	v_add_f32_e32 v133, 1.0, v133
	v_rcp_f32_e32 v143, v133
	s_nop 0
	v_fma_f32 v162, -v133, v143, 1.0
	v_fma_f32 v142, v162, v143, v143
	v_div_fixup_f32 v133, v142, v133, 1.0
	v_mul_f32_e32 v133, 0xbf1b459e, v133
	v_mul_f32_e32 v142, 0x3fb8aa3b, v133
	v_exp_f32_e32 v142, v142
	s_nop 0
	v_sub_f32_e32 v133, 1.0, v142

; __device__ __forceinline__ float sigmoidf_(float x) { return 1.0f / (1.0f + __expf(-x)); }
;     __device__ __forceinline__ void operator()(const f32x4 (&acc)[2][2][4][2], const Unit& u, int wr, int wc, int fr, int fq) const {
;     ...
;                         for (int i = 0; i < 4; ++i) { float xv = acc[ai][bj][m][n][i] + bv[bj][n][i]; float r;
;                             if (type < 2) { const float sg = sigmoidf_(xv); r = -expm1f(-0.606531f * sg); }
;                             else if (type == 2) r = sigmoidf_(xv);
;                             else r = xv;
;                             v[4 * n + i] = (f16)r; }
.LBB0_533:
	v_mul_f32_e32 v134, 0xbfb8aa3b, v142
	v_exp_f32_e32 v134, v134
	s_nop 0
	v_add_f32_e32 v134, 1.0, v134
	v_rcp_f32_e32 v143, v134
	s_nop 0
	v_fma_f32 v162, -v134, v143, 1.0
	v_fma_f32 v142, v162, v143, v143
	v_div_fixup_f32 v134, v142, v134, 1.0
	v_mul_f32_e32 v134, 0xbf1b459e, v134
	v_mul_f32_e32 v142, 0x3fb8aa3b, v134
	v_exp_f32_e32 v142, v142
	s_nop 0
	v_sub_f32_e32 v134, 1.0, v142

; __device__ __forceinline__ float sigmoidf_(float x) { return 1.0f / (1.0f + __expf(-x)); }
;     __device__ __forceinline__ void operator()(const f32x4 (&acc)[2][2][4][2], const Unit& u, int wr, int wc, int fr, int fq) const {
;     ...
;                         for (int i = 0; i < 4; ++i) { float xv = acc[ai][bj][m][n][i] + bv[bj][n][i]; float r;
;                             if (type < 2) { const float sg = sigmoidf_(xv); r = -expm1f(-0.606531f * sg); }
;                             else if (type == 2) r = sigmoidf_(xv);
;                             else r = xv;
;                             v[4 * n + i] = (f16)r; }
.LBB0_539:
	v_mul_f32_e32 v135, 0xbfb8aa3b, v142
	v_exp_f32_e32 v135, v135
	s_nop 0
	v_add_f32_e32 v135, 1.0, v135
	v_rcp_f32_e32 v143, v135
	s_nop 0
	v_fma_f32 v162, -v135, v143, 1.0
	v_fma_f32 v142, v162, v143, v143
	v_div_fixup_f32 v135, v142, v135, 1.0
	v_mul_f32_e32 v135, 0xbf1b459e, v135
	v_mul_f32_e32 v142, 0x3fb8aa3b, v135
	v_exp_f32_e32 v142, v142
	s_nop 0
	v_sub_f32_e32 v135, 1.0, v142

; __device__ __forceinline__ float sigmoidf_(float x) { return 1.0f / (1.0f + __expf(-x)); }
;     __device__ __forceinline__ void operator()(const f32x4 (&acc)[2][2][4][2], const Unit& u, int wr, int wc, int fr, int fq) const {
;     ...
;                         for (int i = 0; i < 4; ++i) { float xv = acc[ai][bj][m][n][i] + bv[bj][n][i]; float r;
;                             if (type < 2) { const float sg = sigmoidf_(xv); r = -expm1f(-0.606531f * sg); }
;                             else if (type == 2) r = sigmoidf_(xv);
;                             else r = xv;
;                             v[4 * n + i] = (f16)r; }
.LBB0_545:
	v_mul_f32_e32 v128, 0xbfb8aa3b, v142
	v_exp_f32_e32 v128, v128
	s_nop 0
	v_add_f32_e32 v128, 1.0, v128
	v_rcp_f32_e32 v143, v128
	s_nop 0
	v_fma_f32 v162, -v128, v143, 1.0
	v_fma_f32 v142, v162, v143, v143
	v_div_fixup_f32 v128, v142, v128, 1.0
	v_mul_f32_e32 v128, 0xbf1b459e, v128
	v_mul_f32_e32 v142, 0x3fb8aa3b, v128
	v_exp_f32_e32 v142, v142
	s_nop 0
	v_sub_f32_e32 v128, 1.0, v142

; __device__ __forceinline__ float sigmoidf_(float x) { return 1.0f / (1.0f + __expf(-x)); }
;     __device__ __forceinline__ void operator()(const f32x4 (&acc)[2][2][4][2], const Unit& u, int wr, int wc, int fr, int fq) const {
;     ...
;                         for (int i = 0; i < 4; ++i) { float xv = acc[ai][bj][m][n][i] + bv[bj][n][i]; float r;
;                             if (type < 2) { const float sg = sigmoidf_(xv); r = -expm1f(-0.606531f * sg); }
;                             else if (type == 2) r = sigmoidf_(xv);
;                             else r = xv;
;                             v[4 * n + i] = (f16)r; }
.LBB0_551:
	v_mul_f32_e32 v129, 0xbfb8aa3b, v142
	v_exp_f32_e32 v129, v129
	s_nop 0
	v_add_f32_e32 v129, 1.0, v129
	v_rcp_f32_e32 v143, v129
	s_nop 0
	v_fma_f32 v162, -v129, v143, 1.0
	v_fma_f32 v142, v162, v143, v143
	v_div_fixup_f32 v129, v142, v129, 1.0
	v_mul_f32_e32 v129, 0xbf1b459e, v129
	v_mul_f32_e32 v142, 0x3fb8aa3b, v129
	v_exp_f32_e32 v142, v142
	s_nop 0
	v_sub_f32_e32 v129, 1.0, v142

; __device__ __forceinline__ float sigmoidf_(float x) { return 1.0f / (1.0f + __expf(-x)); }
;     __device__ __forceinline__ void operator()(const f32x4 (&acc)[2][2][4][2], const Unit& u, int wr, int wc, int fr, int fq) const {
;     ...
;                         for (int i = 0; i < 4; ++i) { float xv = acc[ai][bj][m][n][i] + bv[bj][n][i]; float r;
;                             if (type < 2) { const float sg = sigmoidf_(xv); r = -expm1f(-0.606531f * sg); }
;                             else if (type == 2) r = sigmoidf_(xv);
;                             else r = xv;
;                             v[4 * n + i] = (f16)r; }
.LBB0_557:
	v_mul_f32_e32 v130, 0xbfb8aa3b, v142
	v_exp_f32_e32 v130, v130
	s_nop 0
	v_add_f32_e32 v130, 1.0, v130
	v_rcp_f32_e32 v143, v130
	s_nop 0
	v_fma_f32 v162, -v130, v143, 1.0
	v_fma_f32 v142, v162, v143, v143
	v_div_fixup_f32 v130, v142, v130, 1.0
	v_mul_f32_e32 v130, 0xbf1b459e, v130
	v_mul_f32_e32 v142, 0x3fb8aa3b, v130
	v_exp_f32_e32 v142, v142
	s_nop 0
	v_sub_f32_e32 v130, 1.0, v142

; __device__ __forceinline__ float sigmoidf_(float x) { return 1.0f / (1.0f + __expf(-x)); }
;     __device__ __forceinline__ void operator()(const f32x4 (&acc)[2][2][4][2], const Unit& u, int wr, int wc, int fr, int fq) const {
;     ...
;                         for (int i = 0; i < 4; ++i) { float xv = acc[ai][bj][m][n][i] + bv[bj][n][i]; float r;
;                             if (type < 2) { const float sg = sigmoidf_(xv); r = -expm1f(-0.606531f * sg); }
;                             else if (type == 2) r = sigmoidf_(xv);
;                             else r = xv;
;                             v[4 * n + i] = (f16)r; }
.LBB0_563:
	v_mul_f32_e32 v131, 0xbfb8aa3b, v131
	v_exp_f32_e32 v131, v131
	s_nop 0
	v_add_f32_e32 v131, 1.0, v131
	v_rcp_f32_e32 v143, v131
	s_nop 0
	v_fma_f32 v162, -v131, v143, 1.0
	v_fma_f32 v142, v162, v143, v143
	v_div_fixup_f32 v131, v142, v131, 1.0
	v_mul_f32_e32 v131, 0xbf1b459e, v131
	v_mul_f32_e32 v142, 0x3fb8aa3b, v131
	v_exp_f32_e32 v142, v142
	s_nop 0
	v_sub_f32_e32 v142, 1.0, v142

; __device__ __forceinline__ float sigmoidf_(float x) { return 1.0f / (1.0f + __expf(-x)); }
;     __device__ __forceinline__ void operator()(const f32x4 (&acc)[2][2][4][2], const Unit& u, int wr, int wc, int fr, int fq) const {
;     ...
;                         for (int i = 0; i < 4; ++i) { float xv = acc[ai][bj][m][n][i] + bv[bj][n][i]; float r;
;                             if (type < 2) { const float sg = sigmoidf_(xv); r = -expm1f(-0.606531f * sg); }
;                             else if (type == 2) r = sigmoidf_(xv);
;                             else r = xv;
;                             v[4 * n + i] = (f16)r; }
.LBB0_569:
	v_mul_f32_e32 v124, 0xbfb8aa3b, v128
	v_exp_f32_e32 v124, v124
	s_nop 0
	v_add_f32_e32 v124, 1.0, v124
	v_rcp_f32_e32 v129, v124
	s_nop 0
	v_fma_f32 v131, -v124, v129, 1.0
	v_fma_f32 v128, v131, v129, v129
	v_div_fixup_f32 v124, v128, v124, 1.0
	v_mul_f32_e32 v124, 0xbf1b459e, v124
	v_mul_f32_e32 v128, 0x3fb8aa3b, v124
	v_exp_f32_e32 v128, v128
	s_nop 0
	v_sub_f32_e32 v124, 1.0, v128

; __device__ __forceinline__ float sigmoidf_(float x) { return 1.0f / (1.0f + __expf(-x)); }
;     __device__ __forceinline__ void operator()(const f32x4 (&acc)[2][2][4][2], const Unit& u, int wr, int wc, int fr, int fq) const {
;     ...
;                         for (int i = 0; i < 4; ++i) { float xv = acc[ai][bj][m][n][i] + bv[bj][n][i]; float r;
;                             if (type < 2) { const float sg = sigmoidf_(xv); r = -expm1f(-0.606531f * sg); }
;                             else if (type == 2) r = sigmoidf_(xv);
;                             else r = xv;
;                             v[4 * n + i] = (f16)r; }
.LBB0_575:
	v_mul_f32_e32 v125, 0xbfb8aa3b, v128
	v_exp_f32_e32 v125, v125
	s_nop 0
	v_add_f32_e32 v125, 1.0, v125
	v_rcp_f32_e32 v129, v125
	s_nop 0
	v_fma_f32 v131, -v125, v129, 1.0
	v_fma_f32 v128, v131, v129, v129
	v_div_fixup_f32 v125, v128, v125, 1.0
	v_mul_f32_e32 v125, 0xbf1b459e, v125
	v_mul_f32_e32 v128, 0x3fb8aa3b, v125
	v_exp_f32_e32 v128, v128
	s_nop 0
	v_sub_f32_e32 v125, 1.0, v128

; __device__ __forceinline__ float sigmoidf_(float x) { return 1.0f / (1.0f + __expf(-x)); }
;     __device__ __forceinline__ void operator()(const f32x4 (&acc)[2][2][4][2], const Unit& u, int wr, int wc, int fr, int fq) const {
;     ...
;                         for (int i = 0; i < 4; ++i) { float xv = acc[ai][bj][m][n][i] + bv[bj][n][i]; float r;
;                             if (type < 2) { const float sg = sigmoidf_(xv); r = -expm1f(-0.606531f * sg); }
;                             else if (type == 2) r = sigmoidf_(xv);
;                             else r = xv;
;                             v[4 * n + i] = (f16)r; }
.LBB0_581:
	v_mul_f32_e32 v126, 0xbfb8aa3b, v128
	v_exp_f32_e32 v126, v126
	s_nop 0
	v_add_f32_e32 v126, 1.0, v126
	v_rcp_f32_e32 v129, v126
	s_nop 0
	v_fma_f32 v131, -v126, v129, 1.0
	v_fma_f32 v128, v131, v129, v129
	v_div_fixup_f32 v126, v128, v126, 1.0
	v_mul_f32_e32 v126, 0xbf1b459e, v126
	v_mul_f32_e32 v128, 0x3fb8aa3b, v126
	v_exp_f32_e32 v128, v128
	s_nop 0
	v_sub_f32_e32 v126, 1.0, v128

; __device__ __forceinline__ float sigmoidf_(float x) { return 1.0f / (1.0f + __expf(-x)); }
;     __device__ __forceinline__ void operator()(const f32x4 (&acc)[2][2][4][2], const Unit& u, int wr, int wc, int fr, int fq) const {
;     ...
;                         for (int i = 0; i < 4; ++i) { float xv = acc[ai][bj][m][n][i] + bv[bj][n][i]; float r;
;                             if (type < 2) { const float sg = sigmoidf_(xv); r = -expm1f(-0.606531f * sg); }
;                             else if (type == 2) r = sigmoidf_(xv);
;                             else r = xv;
;                             v[4 * n + i] = (f16)r; }
.LBB0_587:
	v_mul_f32_e32 v127, 0xbfb8aa3b, v128
	v_exp_f32_e32 v127, v127
	s_nop 0
	v_add_f32_e32 v127, 1.0, v127
	v_rcp_f32_e32 v129, v127
	s_nop 0
	v_fma_f32 v131, -v127, v129, 1.0
	v_fma_f32 v128, v131, v129, v129
	v_div_fixup_f32 v127, v128, v127, 1.0
	v_mul_f32_e32 v127, 0xbf1b459e, v127
	v_mul_f32_e32 v128, 0x3fb8aa3b, v127
	v_exp_f32_e32 v128, v128
	s_nop 0
	v_sub_f32_e32 v127, 1.0, v128

; __device__ __forceinline__ float sigmoidf_(float x) { return 1.0f / (1.0f + __expf(-x)); }
;     __device__ __forceinline__ void operator()(const f32x4 (&acc)[2][2][4][2], const Unit& u, int wr, int wc, int fr, int fq) const {
;     ...
;                         for (int i = 0; i < 4; ++i) { float xv = acc[ai][bj][m][n][i] + bv[bj][n][i]; float r;
;                             if (type < 2) { const float sg = sigmoidf_(xv); r = -expm1f(-0.606531f * sg); }
;                             else if (type == 2) r = sigmoidf_(xv);
;                             else r = xv;
;                             v[4 * n + i] = (f16)r; }
.LBB0_593:
	v_mul_f32_e32 v120, 0xbfb8aa3b, v120
	v_exp_f32_e32 v120, v120
	s_nop 0
	v_add_f32_e32 v120, 1.0, v120
	v_rcp_f32_e32 v129, v120
	s_nop 0
	v_fma_f32 v131, -v120, v129, 1.0
	v_fma_f32 v128, v131, v129, v129
	v_div_fixup_f32 v120, v128, v120, 1.0
	v_mul_f32_e32 v120, 0xbf1b459e, v120
	v_mul_f32_e32 v128, 0x3fb8aa3b, v120
	v_exp_f32_e32 v128, v128
	s_nop 0
	v_sub_f32_e32 v128, 1.0, v128

; __device__ __forceinline__ float sigmoidf_(float x) { return 1.0f / (1.0f + __expf(-x)); }
;     __device__ __forceinline__ void operator()(const f32x4 (&acc)[2][2][4][2], const Unit& u, int wr, int wc, int fr, int fq) const {
;     ...
;                         for (int i = 0; i < 4; ++i) { float xv = acc[ai][bj][m][n][i] + bv[bj][n][i]; float r;
;                             if (type < 2) { const float sg = sigmoidf_(xv); r = -expm1f(-0.606531f * sg); }
;                             else if (type == 2) r = sigmoidf_(xv);
;                             else r = xv;
;                             v[4 * n + i] = (f16)r; }
.LBB0_599:
	v_mul_f32_e32 v120, 0xbfb8aa3b, v120
	v_exp_f32_e32 v120, v120
	s_nop 0
	v_add_f32_e32 v120, 1.0, v120
	v_rcp_f32_e32 v129, v120
	s_nop 0
	v_fma_f32 v131, -v120, v129, 1.0
	v_fma_f32 v121, v131, v129, v129
	v_div_fixup_f32 v120, v121, v120, 1.0
	v_mul_f32_e32 v120, 0xbf1b459e, v120
	v_mul_f32_e32 v121, 0x3fb8aa3b, v120
	v_exp_f32_e32 v121, v121
	s_nop 0
	v_sub_f32_e32 v129, 1.0, v121

; __device__ __forceinline__ float sigmoidf_(float x) { return 1.0f / (1.0f + __expf(-x)); }
;     __device__ __forceinline__ void operator()(const f32x4 (&acc)[2][2][4][2], const Unit& u, int wr, int wc, int fr, int fq) const {
;     ...
;                         for (int i = 0; i < 4; ++i) { float xv = acc[ai][bj][m][n][i] + bv[bj][n][i]; float r;
;                             if (type < 2) { const float sg = sigmoidf_(xv); r = -expm1f(-0.606531f * sg); }
;                             else if (type == 2) r = sigmoidf_(xv);
;                             else r = xv;
;                             v[4 * n + i] = (f16)r; }
.LBB0_605:
	v_mul_f32_e32 v120, 0xbfb8aa3b, v120
	v_exp_f32_e32 v120, v120
	s_nop 0
	v_add_f32_e32 v120, 1.0, v120
	v_rcp_f32_e32 v122, v120
	s_nop 0
	v_fma_f32 v131, -v120, v122, 1.0
	v_fma_f32 v121, v131, v122, v122
	v_div_fixup_f32 v120, v121, v120, 1.0
	v_mul_f32_e32 v120, 0xbf1b459e, v120
	v_mul_f32_e32 v121, 0x3fb8aa3b, v120
	v_exp_f32_e32 v121, v121
	s_nop 0
	v_sub_f32_e32 v122, 1.0, v121

; __device__ __forceinline__ float sigmoidf_(float x) { return 1.0f / (1.0f + __expf(-x)); }
;     __device__ __forceinline__ void operator()(const f32x4 (&acc)[2][2][4][2], const Unit& u, int wr, int wc, int fr, int fq) const {
;     ...
;                         for (int i = 0; i < 4; ++i) { float xv = acc[ai][bj][m][n][i] + bv[bj][n][i]; float r;
;                             if (type < 2) { const float sg = sigmoidf_(xv); r = -expm1f(-0.606531f * sg); }
;                             else if (type == 2) r = sigmoidf_(xv);
;                             else r = xv;
;                             v[4 * n + i] = (f16)r; }
.LBB0_611:
	v_mul_f32_e32 v120, 0xbfb8aa3b, v120
	v_exp_f32_e32 v120, v120
	s_nop 0
	v_add_f32_e32 v120, 1.0, v120
	v_rcp_f32_e32 v123, v120
	s_nop 0
	v_fma_f32 v131, -v120, v123, 1.0
	v_fma_f32 v121, v131, v123, v123
	v_div_fixup_f32 v120, v121, v120, 1.0
	v_mul_f32_e32 v120, 0xbf1b459e, v120
	v_mul_f32_e32 v121, 0x3fb8aa3b, v120
	v_exp_f32_e32 v121, v121
	s_nop 0
	v_sub_f32_e32 v123, 1.0, v121

; __device__ __forceinline__ float sigmoidf_(float x) { return 1.0f / (1.0f + __expf(-x)); }
;     __device__ __forceinline__ void operator()(const f32x4 (&acc)[2][2][4][2], const Unit& u, int wr, int wc, int fr, int fq) const {
;     ...
;                         for (int i = 0; i < 4; ++i) { float xv = acc[ai][bj][m][n][i] + bv[bj][n][i]; float r;
;                             if (type < 2) { const float sg = sigmoidf_(xv); r = -expm1f(-0.606531f * sg); }
;                             else if (type == 2) r = sigmoidf_(xv);
;                             else r = xv;
;                             v[4 * n + i] = (f16)r; }
.LBB0_617:
	v_mul_f32_e32 v116, 0xbfb8aa3b, v122
	v_exp_f32_e32 v116, v116
	s_nop 0
	v_add_f32_e32 v116, 1.0, v116
	v_rcp_f32_e32 v123, v116
	s_nop 0
	v_fma_f32 v125, -v116, v123, 1.0
	v_fma_f32 v122, v125, v123, v123
	v_div_fixup_f32 v116, v122, v116, 1.0
	v_mul_f32_e32 v116, 0xbf1b459e, v116
	v_mul_f32_e32 v122, 0x3fb8aa3b, v116
	v_exp_f32_e32 v122, v122
	s_nop 0
	v_sub_f32_e32 v116, 1.0, v122

; __device__ __forceinline__ float sigmoidf_(float x) { return 1.0f / (1.0f + __expf(-x)); }
;     __device__ __forceinline__ void operator()(const f32x4 (&acc)[2][2][4][2], const Unit& u, int wr, int wc, int fr, int fq) const {
;     ...
;                         for (int i = 0; i < 4; ++i) { float xv = acc[ai][bj][m][n][i] + bv[bj][n][i]; float r;
;                             if (type < 2) { const float sg = sigmoidf_(xv); r = -expm1f(-0.606531f * sg); }
;                             else if (type == 2) r = sigmoidf_(xv);
;                             else r = xv;
;                             v[4 * n + i] = (f16)r; }
.LBB0_623:
	v_mul_f32_e32 v117, 0xbfb8aa3b, v122
	v_exp_f32_e32 v117, v117
	s_nop 0
	v_add_f32_e32 v117, 1.0, v117
	v_rcp_f32_e32 v123, v117
	s_nop 0
	v_fma_f32 v125, -v117, v123, 1.0
	v_fma_f32 v122, v125, v123, v123
	v_div_fixup_f32 v117, v122, v117, 1.0
	v_mul_f32_e32 v117, 0xbf1b459e, v117
	v_mul_f32_e32 v122, 0x3fb8aa3b, v117
	v_exp_f32_e32 v122, v122
	s_nop 0
	v_sub_f32_e32 v117, 1.0, v122

; __device__ __forceinline__ float sigmoidf_(float x) { return 1.0f / (1.0f + __expf(-x)); }
;     __device__ __forceinline__ void operator()(const f32x4 (&acc)[2][2][4][2], const Unit& u, int wr, int wc, int fr, int fq) const {
;     ...
;                         for (int i = 0; i < 4; ++i) { float xv = acc[ai][bj][m][n][i] + bv[bj][n][i]; float r;
;                             if (type < 2) { const float sg = sigmoidf_(xv); r = -expm1f(-0.606531f * sg); }
;                             else if (type == 2) r = sigmoidf_(xv);
;                             else r = xv;
;                             v[4 * n + i] = (f16)r; }
.LBB0_629:
	v_mul_f32_e32 v118, 0xbfb8aa3b, v122
	v_exp_f32_e32 v118, v118
	s_nop 0
	v_add_f32_e32 v118, 1.0, v118
	v_rcp_f32_e32 v123, v118
	s_nop 0
	v_fma_f32 v125, -v118, v123, 1.0
	v_fma_f32 v122, v125, v123, v123
	v_div_fixup_f32 v118, v122, v118, 1.0
	v_mul_f32_e32 v118, 0xbf1b459e, v118
	v_mul_f32_e32 v122, 0x3fb8aa3b, v118
	v_exp_f32_e32 v122, v122
	s_nop 0
	v_sub_f32_e32 v118, 1.0, v122

; __device__ __forceinline__ float sigmoidf_(float x) { return 1.0f / (1.0f + __expf(-x)); }
;     __device__ __forceinline__ void operator()(const f32x4 (&acc)[2][2][4][2], const Unit& u, int wr, int wc, int fr, int fq) const {
;     ...
;                         for (int i = 0; i < 4; ++i) { float xv = acc[ai][bj][m][n][i] + bv[bj][n][i]; float r;
;                             if (type < 2) { const float sg = sigmoidf_(xv); r = -expm1f(-0.606531f * sg); }
;                             else if (type == 2) r = sigmoidf_(xv);
;                             else r = xv;
;                             v[4 * n + i] = (f16)r; }
.LBB0_635:
	v_mul_f32_e32 v119, 0xbfb8aa3b, v122
	v_exp_f32_e32 v119, v119
	s_nop 0
	v_add_f32_e32 v119, 1.0, v119
	v_rcp_f32_e32 v123, v119
	s_nop 0
	v_fma_f32 v125, -v119, v123, 1.0
	v_fma_f32 v122, v125, v123, v123
	v_div_fixup_f32 v119, v122, v119, 1.0
	v_mul_f32_e32 v119, 0xbf1b459e, v119
	v_mul_f32_e32 v122, 0x3fb8aa3b, v119
	v_exp_f32_e32 v122, v122
	s_nop 0
	v_sub_f32_e32 v119, 1.0, v122

; __device__ __forceinline__ float sigmoidf_(float x) { return 1.0f / (1.0f + __expf(-x)); }
;     __device__ __forceinline__ void operator()(const f32x4 (&acc)[2][2][4][2], const Unit& u, int wr, int wc, int fr, int fq) const {
;     ...
;                         for (int i = 0; i < 4; ++i) { float xv = acc[ai][bj][m][n][i] + bv[bj][n][i]; float r;
;                             if (type < 2) { const float sg = sigmoidf_(xv); r = -expm1f(-0.606531f * sg); }
;                             else if (type == 2) r = sigmoidf_(xv);
;                             else r = xv;
;                             v[4 * n + i] = (f16)r; }
.LBB0_641:
	v_mul_f32_e32 v112, 0xbfb8aa3b, v122
	v_exp_f32_e32 v112, v112
	s_nop 0
	v_add_f32_e32 v112, 1.0, v112
	v_rcp_f32_e32 v123, v112
	s_nop 0
	v_fma_f32 v125, -v112, v123, 1.0
	v_fma_f32 v122, v125, v123, v123
	v_div_fixup_f32 v112, v122, v112, 1.0
	v_mul_f32_e32 v112, 0xbf1b459e, v112
	v_mul_f32_e32 v122, 0x3fb8aa3b, v112
	v_exp_f32_e32 v122, v122
	s_nop 0
	v_sub_f32_e32 v112, 1.0, v122

; __device__ __forceinline__ float sigmoidf_(float x) { return 1.0f / (1.0f + __expf(-x)); }
;     __device__ __forceinline__ void operator()(const f32x4 (&acc)[2][2][4][2], const Unit& u, int wr, int wc, int fr, int fq) const {
;     ...
;                         for (int i = 0; i < 4; ++i) { float xv = acc[ai][bj][m][n][i] + bv[bj][n][i]; float r;
;                             if (type < 2) { const float sg = sigmoidf_(xv); r = -expm1f(-0.606531f * sg); }
;                             else if (type == 2) r = sigmoidf_(xv);
;                             else r = xv;
;                             v[4 * n + i] = (f16)r; }
.LBB0_647:
	v_mul_f32_e32 v113, 0xbfb8aa3b, v122
	v_exp_f32_e32 v113, v113
	s_nop 0
	v_add_f32_e32 v113, 1.0, v113
	v_rcp_f32_e32 v123, v113
	s_nop 0
	v_fma_f32 v125, -v113, v123, 1.0
	v_fma_f32 v122, v125, v123, v123
	v_div_fixup_f32 v113, v122, v113, 1.0
	v_mul_f32_e32 v113, 0xbf1b459e, v113
	v_mul_f32_e32 v122, 0x3fb8aa3b, v113
	v_exp_f32_e32 v122, v122
	s_nop 0
	v_sub_f32_e32 v113, 1.0, v122

; __device__ __forceinline__ float sigmoidf_(float x) { return 1.0f / (1.0f + __expf(-x)); }
;     __device__ __forceinline__ void operator()(const f32x4 (&acc)[2][2][4][2], const Unit& u, int wr, int wc, int fr, int fq) const {
;     ...
;                         for (int i = 0; i < 4; ++i) { float xv = acc[ai][bj][m][n][i] + bv[bj][n][i]; float r;
;                             if (type < 2) { const float sg = sigmoidf_(xv); r = -expm1f(-0.606531f * sg); }
;                             else if (type == 2) r = sigmoidf_(xv);
;                             else r = xv;
;                             v[4 * n + i] = (f16)r; }
.LBB0_653:
	v_mul_f32_e32 v114, 0xbfb8aa3b, v122
	v_exp_f32_e32 v114, v114
	s_nop 0
	v_add_f32_e32 v114, 1.0, v114
	v_rcp_f32_e32 v123, v114
	s_nop 0
	v_fma_f32 v125, -v114, v123, 1.0
	v_fma_f32 v122, v125, v123, v123
	v_div_fixup_f32 v114, v122, v114, 1.0
	v_mul_f32_e32 v114, 0xbf1b459e, v114
	v_mul_f32_e32 v122, 0x3fb8aa3b, v114
	v_exp_f32_e32 v122, v122
	s_nop 0
	v_sub_f32_e32 v114, 1.0, v122

; __device__ __forceinline__ float sigmoidf_(float x) { return 1.0f / (1.0f + __expf(-x)); }
;     __device__ __forceinline__ void operator()(const f32x4 (&acc)[2][2][4][2], const Unit& u, int wr, int wc, int fr, int fq) const {
;     ...
;                         for (int i = 0; i < 4; ++i) { float xv = acc[ai][bj][m][n][i] + bv[bj][n][i]; float r;
;                             if (type < 2) { const float sg = sigmoidf_(xv); r = -expm1f(-0.606531f * sg); }
;                             else if (type == 2) r = sigmoidf_(xv);
;                             else r = xv;
;                             v[4 * n + i] = (f16)r; }
.LBB0_659:
	v_mul_f32_e32 v115, 0xbfb8aa3b, v115
	v_exp_f32_e32 v115, v115
	s_nop 0
	v_add_f32_e32 v115, 1.0, v115
	v_rcp_f32_e32 v123, v115
	s_nop 0
	v_fma_f32 v125, -v115, v123, 1.0
	v_fma_f32 v122, v125, v123, v123
	v_div_fixup_f32 v115, v122, v115, 1.0
	v_mul_f32_e32 v115, 0xbf1b459e, v115
	v_mul_f32_e32 v122, 0x3fb8aa3b, v115
	v_exp_f32_e32 v122, v122
	s_nop 0
	v_sub_f32_e32 v122, 1.0, v122

; __device__ __forceinline__ float sigmoidf_(float x) { return 1.0f / (1.0f + __expf(-x)); }
;     __device__ __forceinline__ void operator()(const f32x4 (&acc)[2][2][4][2], const Unit& u, int wr, int wc, int fr, int fq) const {
;     ...
;                         for (int i = 0; i < 4; ++i) { float xv = acc[ai][bj][m][n][i] + bv[bj][n][i]; float r;
;                             if (type < 2) { const float sg = sigmoidf_(xv); r = -expm1f(-0.606531f * sg); }
;                             else if (type == 2) r = sigmoidf_(xv);
;                             else r = xv;
;                             v[4 * n + i] = (f16)r; }
.LBB0_665:
	v_mul_f32_e32 v108, 0xbfb8aa3b, v112
	v_exp_f32_e32 v108, v108
	s_nop 0
	v_add_f32_e32 v108, 1.0, v108
	v_rcp_f32_e32 v113, v108
	s_nop 0
	v_fma_f32 v115, -v108, v113, 1.0
	v_fma_f32 v112, v115, v113, v113
	v_div_fixup_f32 v108, v112, v108, 1.0
	v_mul_f32_e32 v108, 0xbf1b459e, v108
	v_mul_f32_e32 v112, 0x3fb8aa3b, v108
	v_exp_f32_e32 v112, v112
	s_nop 0
	v_sub_f32_e32 v108, 1.0, v112

; __device__ __forceinline__ float sigmoidf_(float x) { return 1.0f / (1.0f + __expf(-x)); }
;     __device__ __forceinline__ void operator()(const f32x4 (&acc)[2][2][4][2], const Unit& u, int wr, int wc, int fr, int fq) const {
;     ...
;                         for (int i = 0; i < 4; ++i) { float xv = acc[ai][bj][m][n][i] + bv[bj][n][i]; float r;
;                             if (type < 2) { const float sg = sigmoidf_(xv); r = -expm1f(-0.606531f * sg); }
;                             else if (type == 2) r = sigmoidf_(xv);
;                             else r = xv;
;                             v[4 * n + i] = (f16)r; }
.LBB0_671:
	v_mul_f32_e32 v109, 0xbfb8aa3b, v112
	v_exp_f32_e32 v109, v109
	s_nop 0
	v_add_f32_e32 v109, 1.0, v109
	v_rcp_f32_e32 v113, v109
	s_nop 0
	v_fma_f32 v115, -v109, v113, 1.0
	v_fma_f32 v112, v115, v113, v113
	v_div_fixup_f32 v109, v112, v109, 1.0
	v_mul_f32_e32 v109, 0xbf1b459e, v109
	v_mul_f32_e32 v112, 0x3fb8aa3b, v109
	v_exp_f32_e32 v112, v112
	s_nop 0
	v_sub_f32_e32 v109, 1.0, v112

; __device__ __forceinline__ float sigmoidf_(float x) { return 1.0f / (1.0f + __expf(-x)); }
;     __device__ __forceinline__ void operator()(const f32x4 (&acc)[2][2][4][2], const Unit& u, int wr, int wc, int fr, int fq) const {
;     ...
;                         for (int i = 0; i < 4; ++i) { float xv = acc[ai][bj][m][n][i] + bv[bj][n][i]; float r;
;                             if (type < 2) { const float sg = sigmoidf_(xv); r = -expm1f(-0.606531f * sg); }
;                             else if (type == 2) r = sigmoidf_(xv);
;                             else r = xv;
;                             v[4 * n + i] = (f16)r; }
.LBB0_677:
	v_mul_f32_e32 v110, 0xbfb8aa3b, v112
	v_exp_f32_e32 v110, v110
	s_nop 0
	v_add_f32_e32 v110, 1.0, v110
	v_rcp_f32_e32 v113, v110
	s_nop 0
	v_fma_f32 v115, -v110, v113, 1.0
	v_fma_f32 v112, v115, v113, v113
	v_div_fixup_f32 v110, v112, v110, 1.0
	v_mul_f32_e32 v110, 0xbf1b459e, v110
	v_mul_f32_e32 v112, 0x3fb8aa3b, v110
	v_exp_f32_e32 v112, v112
	s_nop 0
	v_sub_f32_e32 v110, 1.0, v112

; __device__ __forceinline__ float sigmoidf_(float x) { return 1.0f / (1.0f + __expf(-x)); }
;     __device__ __forceinline__ void operator()(const f32x4 (&acc)[2][2][4][2], const Unit& u, int wr, int wc, int fr, int fq) const {
;     ...
;                         for (int i = 0; i < 4; ++i) { float xv = acc[ai][bj][m][n][i] + bv[bj][n][i]; float r;
;                             if (type < 2) { const float sg = sigmoidf_(xv); r = -expm1f(-0.606531f * sg); }
;                             else if (type == 2) r = sigmoidf_(xv);
;                             else r = xv;
;                             v[4 * n + i] = (f16)r; }
.LBB0_683:
	v_mul_f32_e32 v111, 0xbfb8aa3b, v112
	v_exp_f32_e32 v111, v111
	s_nop 0
	v_add_f32_e32 v111, 1.0, v111
	v_rcp_f32_e32 v113, v111
	s_nop 0
	v_fma_f32 v115, -v111, v113, 1.0
	v_fma_f32 v112, v115, v113, v113
	v_div_fixup_f32 v111, v112, v111, 1.0
	v_mul_f32_e32 v111, 0xbf1b459e, v111
	v_mul_f32_e32 v112, 0x3fb8aa3b, v111
	v_exp_f32_e32 v112, v112
	s_nop 0
	v_sub_f32_e32 v111, 1.0, v112

; __device__ __forceinline__ float sigmoidf_(float x) { return 1.0f / (1.0f + __expf(-x)); }
;     __device__ __forceinline__ void operator()(const f32x4 (&acc)[2][2][4][2], const Unit& u, int wr, int wc, int fr, int fq) const {
;     ...
;                         for (int i = 0; i < 4; ++i) { float xv = acc[ai][bj][m][n][i] + bv[bj][n][i]; float r;
;                             if (type < 2) { const float sg = sigmoidf_(xv); r = -expm1f(-0.606531f * sg); }
;                             else if (type == 2) r = sigmoidf_(xv);
;                             else r = xv;
;                             v[4 * n + i] = (f16)r; }
.LBB0_689:
	v_mul_f32_e32 v104, 0xbfb8aa3b, v104
	v_exp_f32_e32 v104, v104
	s_nop 0
	v_add_f32_e32 v104, 1.0, v104
	v_rcp_f32_e32 v113, v104
	s_nop 0
	v_fma_f32 v115, -v104, v113, 1.0
	v_fma_f32 v112, v115, v113, v113
	v_div_fixup_f32 v104, v112, v104, 1.0
	v_mul_f32_e32 v104, 0xbf1b459e, v104
	v_mul_f32_e32 v112, 0x3fb8aa3b, v104
	v_exp_f32_e32 v112, v112
	s_nop 0
	v_sub_f32_e32 v112, 1.0, v112

; __device__ __forceinline__ float sigmoidf_(float x) { return 1.0f / (1.0f + __expf(-x)); }
;     __device__ __forceinline__ void operator()(const f32x4 (&acc)[2][2][4][2], const Unit& u, int wr, int wc, int fr, int fq) const {
;     ...
;                         for (int i = 0; i < 4; ++i) { float xv = acc[ai][bj][m][n][i] + bv[bj][n][i]; float r;
;                             if (type < 2) { const float sg = sigmoidf_(xv); r = -expm1f(-0.606531f * sg); }
;                             else if (type == 2) r = sigmoidf_(xv);
;                             else r = xv;
;                             v[4 * n + i] = (f16)r; }
.LBB0_695:
	v_mul_f32_e32 v104, 0xbfb8aa3b, v104
	v_exp_f32_e32 v104, v104
	s_nop 0
	v_add_f32_e32 v104, 1.0, v104
	v_rcp_f32_e32 v113, v104
	s_nop 0
	v_fma_f32 v115, -v104, v113, 1.0
	v_fma_f32 v105, v115, v113, v113
	v_div_fixup_f32 v104, v105, v104, 1.0
	v_mul_f32_e32 v104, 0xbf1b459e, v104
	v_mul_f32_e32 v105, 0x3fb8aa3b, v104
	v_exp_f32_e32 v105, v105
	s_nop 0
	v_sub_f32_e32 v113, 1.0, v105

; __device__ __forceinline__ float sigmoidf_(float x) { return 1.0f / (1.0f + __expf(-x)); }
;     __device__ __forceinline__ void operator()(const f32x4 (&acc)[2][2][4][2], const Unit& u, int wr, int wc, int fr, int fq) const {
;     ...
;                         for (int i = 0; i < 4; ++i) { float xv = acc[ai][bj][m][n][i] + bv[bj][n][i]; float r;
;                             if (type < 2) { const float sg = sigmoidf_(xv); r = -expm1f(-0.606531f * sg); }
;                             else if (type == 2) r = sigmoidf_(xv);
;                             else r = xv;
;                             v[4 * n + i] = (f16)r; }
.LBB0_701:
	v_mul_f32_e32 v104, 0xbfb8aa3b, v104
	v_exp_f32_e32 v104, v104
	s_nop 0
	v_add_f32_e32 v104, 1.0, v104
	v_rcp_f32_e32 v106, v104
	s_nop 0
	v_fma_f32 v115, -v104, v106, 1.0
	v_fma_f32 v105, v115, v106, v106
	v_div_fixup_f32 v104, v105, v104, 1.0
	v_mul_f32_e32 v104, 0xbf1b459e, v104
	v_mul_f32_e32 v105, 0x3fb8aa3b, v104
	v_exp_f32_e32 v105, v105
	s_nop 0
	v_sub_f32_e32 v106, 1.0, v105

; __device__ __forceinline__ float sigmoidf_(float x) { return 1.0f / (1.0f + __expf(-x)); }
;     __device__ __forceinline__ void operator()(const f32x4 (&acc)[2][2][4][2], const Unit& u, int wr, int wc, int fr, int fq) const {
;     ...
;                         for (int i = 0; i < 4; ++i) { float xv = acc[ai][bj][m][n][i] + bv[bj][n][i]; float r;
;                             if (type < 2) { const float sg = sigmoidf_(xv); r = -expm1f(-0.606531f * sg); }
;                             else if (type == 2) r = sigmoidf_(xv);
;                             else r = xv;
;                             v[4 * n + i] = (f16)r; }
.LBB0_707:
	v_mul_f32_e32 v104, 0xbfb8aa3b, v104
	v_exp_f32_e32 v104, v104
	s_nop 0
	v_add_f32_e32 v104, 1.0, v104
	v_rcp_f32_e32 v107, v104
	s_nop 0
	v_fma_f32 v115, -v104, v107, 1.0
	v_fma_f32 v105, v115, v107, v107
	v_div_fixup_f32 v104, v105, v104, 1.0
	v_mul_f32_e32 v104, 0xbf1b459e, v104
	v_mul_f32_e32 v105, 0x3fb8aa3b, v104
	v_exp_f32_e32 v105, v105
	s_nop 0
	v_sub_f32_e32 v107, 1.0, v105

; __device__ __forceinline__ float sigmoidf_(float x) { return 1.0f / (1.0f + __expf(-x)); }
;     __device__ __forceinline__ void operator()(const f32x4 (&acc)[2][2][4][2], const Unit& u, int wr, int wc, int fr, int fq) const {
;     ...
;                         for (int i = 0; i < 4; ++i) { float xv = acc[ai][bj][m][n][i] + bv[bj][n][i]; float r;
;                             if (type < 2) { const float sg = sigmoidf_(xv); r = -expm1f(-0.606531f * sg); }
;                             else if (type == 2) r = sigmoidf_(xv);
;                             else r = xv;
;                             v[4 * n + i] = (f16)r; }
.LBB0_713:
	v_mul_f32_e32 v100, 0xbfb8aa3b, v106
	v_exp_f32_e32 v100, v100
	s_nop 0
	v_add_f32_e32 v100, 1.0, v100
	v_rcp_f32_e32 v107, v100
	s_nop 0
	v_fma_f32 v109, -v100, v107, 1.0
	v_fma_f32 v106, v109, v107, v107
	v_div_fixup_f32 v100, v106, v100, 1.0
	v_mul_f32_e32 v100, 0xbf1b459e, v100
	v_mul_f32_e32 v106, 0x3fb8aa3b, v100
	v_exp_f32_e32 v106, v106
	s_nop 0
	v_sub_f32_e32 v100, 1.0, v106

; __device__ __forceinline__ float sigmoidf_(float x) { return 1.0f / (1.0f + __expf(-x)); }
;     __device__ __forceinline__ void operator()(const f32x4 (&acc)[2][2][4][2], const Unit& u, int wr, int wc, int fr, int fq) const {
;     ...
;                         for (int i = 0; i < 4; ++i) { float xv = acc[ai][bj][m][n][i] + bv[bj][n][i]; float r;
;                             if (type < 2) { const float sg = sigmoidf_(xv); r = -expm1f(-0.606531f * sg); }
;                             else if (type == 2) r = sigmoidf_(xv);
;                             else r = xv;
;                             v[4 * n + i] = (f16)r; }
.LBB0_719:
	v_mul_f32_e32 v101, 0xbfb8aa3b, v106
	v_exp_f32_e32 v101, v101
	s_nop 0
	v_add_f32_e32 v101, 1.0, v101
	v_rcp_f32_e32 v107, v101
	s_nop 0
	v_fma_f32 v109, -v101, v107, 1.0
	v_fma_f32 v106, v109, v107, v107
	v_div_fixup_f32 v101, v106, v101, 1.0
	v_mul_f32_e32 v101, 0xbf1b459e, v101
	v_mul_f32_e32 v106, 0x3fb8aa3b, v101
	v_exp_f32_e32 v106, v106
	s_nop 0
	v_sub_f32_e32 v101, 1.0, v106

; __device__ __forceinline__ float sigmoidf_(float x) { return 1.0f / (1.0f + __expf(-x)); }
;     __device__ __forceinline__ void operator()(const f32x4 (&acc)[2][2][4][2], const Unit& u, int wr, int wc, int fr, int fq) const {
;     ...
;                         for (int i = 0; i < 4; ++i) { float xv = acc[ai][bj][m][n][i] + bv[bj][n][i]; float r;
;                             if (type < 2) { const float sg = sigmoidf_(xv); r = -expm1f(-0.606531f * sg); }
;                             else if (type == 2) r = sigmoidf_(xv);
;                             else r = xv;
;                             v[4 * n + i] = (f16)r; }
.LBB0_725:
	v_mul_f32_e32 v102, 0xbfb8aa3b, v106
	v_exp_f32_e32 v102, v102
	s_nop 0
	v_add_f32_e32 v102, 1.0, v102
	v_rcp_f32_e32 v107, v102
	s_nop 0
	v_fma_f32 v109, -v102, v107, 1.0
	v_fma_f32 v106, v109, v107, v107
	v_div_fixup_f32 v102, v106, v102, 1.0
	v_mul_f32_e32 v102, 0xbf1b459e, v102
	v_mul_f32_e32 v106, 0x3fb8aa3b, v102
	v_exp_f32_e32 v106, v106
	s_nop 0
	v_sub_f32_e32 v102, 1.0, v106

; __device__ __forceinline__ float sigmoidf_(float x) { return 1.0f / (1.0f + __expf(-x)); }
;     __device__ __forceinline__ void operator()(const f32x4 (&acc)[2][2][4][2], const Unit& u, int wr, int wc, int fr, int fq) const {
;     ...
;                         for (int i = 0; i < 4; ++i) { float xv = acc[ai][bj][m][n][i] + bv[bj][n][i]; float r;
;                             if (type < 2) { const float sg = sigmoidf_(xv); r = -expm1f(-0.606531f * sg); }
;                             else if (type == 2) r = sigmoidf_(xv);
;                             else r = xv;
;                             v[4 * n + i] = (f16)r; }
.LBB0_731:
	v_mul_f32_e32 v103, 0xbfb8aa3b, v106
	v_exp_f32_e32 v103, v103
	s_nop 0
	v_add_f32_e32 v103, 1.0, v103
	v_rcp_f32_e32 v107, v103
	s_nop 0
	v_fma_f32 v109, -v103, v107, 1.0
	v_fma_f32 v106, v109, v107, v107
	v_div_fixup_f32 v103, v106, v103, 1.0
	v_mul_f32_e32 v103, 0xbf1b459e, v103
	v_mul_f32_e32 v106, 0x3fb8aa3b, v103
	v_exp_f32_e32 v106, v106
	s_nop 0
	v_sub_f32_e32 v103, 1.0, v106

; __device__ __forceinline__ float sigmoidf_(float x) { return 1.0f / (1.0f + __expf(-x)); }
;     __device__ __forceinline__ void operator()(const f32x4 (&acc)[2][2][4][2], const Unit& u, int wr, int wc, int fr, int fq) const {
;     ...
;                         for (int i = 0; i < 4; ++i) { float xv = acc[ai][bj][m][n][i] + bv[bj][n][i]; float r;
;                             if (type < 2) { const float sg = sigmoidf_(xv); r = -expm1f(-0.606531f * sg); }
;                             else if (type == 2) r = sigmoidf_(xv);
;                             else r = xv;
;                             v[4 * n + i] = (f16)r; }
.LBB0_737:
	v_mul_f32_e32 v96, 0xbfb8aa3b, v106
	v_exp_f32_e32 v96, v96
	s_nop 0
	v_add_f32_e32 v96, 1.0, v96
	v_rcp_f32_e32 v107, v96
	s_nop 0
	v_fma_f32 v109, -v96, v107, 1.0
	v_fma_f32 v106, v109, v107, v107
	v_div_fixup_f32 v96, v106, v96, 1.0
	v_mul_f32_e32 v96, 0xbf1b459e, v96
	v_mul_f32_e32 v106, 0x3fb8aa3b, v96
	v_exp_f32_e32 v106, v106
	s_nop 0
	v_sub_f32_e32 v96, 1.0, v106

; __device__ __forceinline__ float sigmoidf_(float x) { return 1.0f / (1.0f + __expf(-x)); }
;     __device__ __forceinline__ void operator()(const f32x4 (&acc)[2][2][4][2], const Unit& u, int wr, int wc, int fr, int fq) const {
;     ...
;                         for (int i = 0; i < 4; ++i) { float xv = acc[ai][bj][m][n][i] + bv[bj][n][i]; float r;
;                             if (type < 2) { const float sg = sigmoidf_(xv); r = -expm1f(-0.606531f * sg); }
;                             else if (type == 2) r = sigmoidf_(xv);
;                             else r = xv;
;                             v[4 * n + i] = (f16)r; }
.LBB0_743:
	v_mul_f32_e32 v97, 0xbfb8aa3b, v106
	v_exp_f32_e32 v97, v97
	s_nop 0
	v_add_f32_e32 v97, 1.0, v97
	v_rcp_f32_e32 v107, v97
	s_nop 0
	v_fma_f32 v109, -v97, v107, 1.0
	v_fma_f32 v106, v109, v107, v107
	v_div_fixup_f32 v97, v106, v97, 1.0
	v_mul_f32_e32 v97, 0xbf1b459e, v97
	v_mul_f32_e32 v106, 0x3fb8aa3b, v97
	v_exp_f32_e32 v106, v106
	s_nop 0
	v_sub_f32_e32 v97, 1.0, v106

; __device__ __forceinline__ float sigmoidf_(float x) { return 1.0f / (1.0f + __expf(-x)); }
;     __device__ __forceinline__ void operator()(const f32x4 (&acc)[2][2][4][2], const Unit& u, int wr, int wc, int fr, int fq) const {
;     ...
;                         for (int i = 0; i < 4; ++i) { float xv = acc[ai][bj][m][n][i] + bv[bj][n][i]; float r;
;                             if (type < 2) { const float sg = sigmoidf_(xv); r = -expm1f(-0.606531f * sg); }
;                             else if (type == 2) r = sigmoidf_(xv);
;                             else r = xv;
;                             v[4 * n + i] = (f16)r; }
.LBB0_749:
	v_mul_f32_e32 v98, 0xbfb8aa3b, v106
	v_exp_f32_e32 v98, v98
	s_nop 0
	v_add_f32_e32 v98, 1.0, v98
	v_rcp_f32_e32 v107, v98
	s_nop 0
	v_fma_f32 v109, -v98, v107, 1.0
	v_fma_f32 v106, v109, v107, v107
	v_div_fixup_f32 v98, v106, v98, 1.0
	v_mul_f32_e32 v98, 0xbf1b459e, v98
	v_mul_f32_e32 v106, 0x3fb8aa3b, v98
	v_exp_f32_e32 v106, v106
	s_nop 0
	v_sub_f32_e32 v98, 1.0, v106

; __device__ __forceinline__ float sigmoidf_(float x) { return 1.0f / (1.0f + __expf(-x)); }
;     __device__ __forceinline__ void operator()(const f32x4 (&acc)[2][2][4][2], const Unit& u, int wr, int wc, int fr, int fq) const {
;     ...
;                         for (int i = 0; i < 4; ++i) { float xv = acc[ai][bj][m][n][i] + bv[bj][n][i]; float r;
;                             if (type < 2) { const float sg = sigmoidf_(xv); r = -expm1f(-0.606531f * sg); }
;                             else if (type == 2) r = sigmoidf_(xv);
;                             else r = xv;
;                             v[4 * n + i] = (f16)r; }
.LBB0_755:
	v_mul_f32_e32 v99, 0xbfb8aa3b, v99
	v_exp_f32_e32 v99, v99
	s_nop 0
	v_add_f32_e32 v99, 1.0, v99
	v_rcp_f32_e32 v107, v99
	s_nop 0
	v_fma_f32 v109, -v99, v107, 1.0
	v_fma_f32 v106, v109, v107, v107
	v_div_fixup_f32 v99, v106, v99, 1.0
	v_mul_f32_e32 v99, 0xbf1b459e, v99
	v_mul_f32_e32 v106, 0x3fb8aa3b, v99
	v_exp_f32_e32 v106, v106
	s_nop 0
	v_sub_f32_e32 v106, 1.0, v106

; __device__ __forceinline__ float sigmoidf_(float x) { return 1.0f / (1.0f + __expf(-x)); }
;     __device__ __forceinline__ void operator()(const f32x4 (&acc)[2][2][4][2], const Unit& u, int wr, int wc, int fr, int fq) const {
;     ...
;                         for (int i = 0; i < 4; ++i) { float xv = acc[ai][bj][m][n][i] + bv[bj][n][i]; float r;
;                             if (type < 2) { const float sg = sigmoidf_(xv); r = -expm1f(-0.606531f * sg); }
;                             else if (type == 2) r = sigmoidf_(xv);
;                             else r = xv;
;                             v[4 * n + i] = (f16)r; }
.LBB0_761:
	v_mul_f32_e32 v92, 0xbfb8aa3b, v96
	v_exp_f32_e32 v92, v92
	s_nop 0
	v_add_f32_e32 v92, 1.0, v92
	v_rcp_f32_e32 v97, v92
	s_nop 0
	v_fma_f32 v99, -v92, v97, 1.0
	v_fma_f32 v96, v99, v97, v97
	v_div_fixup_f32 v92, v96, v92, 1.0
	v_mul_f32_e32 v92, 0xbf1b459e, v92
	v_mul_f32_e32 v96, 0x3fb8aa3b, v92
	v_exp_f32_e32 v96, v96
	s_nop 0
	v_sub_f32_e32 v92, 1.0, v96

; __device__ __forceinline__ float sigmoidf_(float x) { return 1.0f / (1.0f + __expf(-x)); }
;     __device__ __forceinline__ void operator()(const f32x4 (&acc)[2][2][4][2], const Unit& u, int wr, int wc, int fr, int fq) const {
;     ...
;                         for (int i = 0; i < 4; ++i) { float xv = acc[ai][bj][m][n][i] + bv[bj][n][i]; float r;
;                             if (type < 2) { const float sg = sigmoidf_(xv); r = -expm1f(-0.606531f * sg); }
;                             else if (type == 2) r = sigmoidf_(xv);
;                             else r = xv;
;                             v[4 * n + i] = (f16)r; }
.LBB0_767:
	v_mul_f32_e32 v93, 0xbfb8aa3b, v96
	v_exp_f32_e32 v93, v93
	s_nop 0
	v_add_f32_e32 v93, 1.0, v93
	v_rcp_f32_e32 v97, v93
	s_nop 0
	v_fma_f32 v99, -v93, v97, 1.0
	v_fma_f32 v96, v99, v97, v97
	v_div_fixup_f32 v93, v96, v93, 1.0
	v_mul_f32_e32 v93, 0xbf1b459e, v93
	v_mul_f32_e32 v96, 0x3fb8aa3b, v93
	v_exp_f32_e32 v96, v96
	s_nop 0
	v_sub_f32_e32 v93, 1.0, v96

; __device__ __forceinline__ float sigmoidf_(float x) { return 1.0f / (1.0f + __expf(-x)); }
;     __device__ __forceinline__ void operator()(const f32x4 (&acc)[2][2][4][2], const Unit& u, int wr, int wc, int fr, int fq) const {
;     ...
;                         for (int i = 0; i < 4; ++i) { float xv = acc[ai][bj][m][n][i] + bv[bj][n][i]; float r;
;                             if (type < 2) { const float sg = sigmoidf_(xv); r = -expm1f(-0.606531f * sg); }
;                             else if (type == 2) r = sigmoidf_(xv);
;                             else r = xv;
;                             v[4 * n + i] = (f16)r; }
.LBB0_773:
	v_mul_f32_e32 v94, 0xbfb8aa3b, v96
	v_exp_f32_e32 v94, v94
	s_nop 0
	v_add_f32_e32 v94, 1.0, v94
	v_rcp_f32_e32 v97, v94
	s_nop 0
	v_fma_f32 v99, -v94, v97, 1.0
	v_fma_f32 v96, v99, v97, v97
	v_div_fixup_f32 v94, v96, v94, 1.0
	v_mul_f32_e32 v94, 0xbf1b459e, v94
	v_mul_f32_e32 v96, 0x3fb8aa3b, v94
	v_exp_f32_e32 v96, v96
	s_nop 0
	v_sub_f32_e32 v94, 1.0, v96

; __device__ __forceinline__ float sigmoidf_(float x) { return 1.0f / (1.0f + __expf(-x)); }
;     __device__ __forceinline__ void operator()(const f32x4 (&acc)[2][2][4][2], const Unit& u, int wr, int wc, int fr, int fq) const {
;     ...
;                         for (int i = 0; i < 4; ++i) { float xv = acc[ai][bj][m][n][i] + bv[bj][n][i]; float r;
;                             if (type < 2) { const float sg = sigmoidf_(xv); r = -expm1f(-0.606531f * sg); }
;                             else if (type == 2) r = sigmoidf_(xv);
;                             else r = xv;
;                             v[4 * n + i] = (f16)r; }
.LBB0_779:
	v_mul_f32_e32 v95, 0xbfb8aa3b, v96
	v_exp_f32_e32 v95, v95
	s_nop 0
	v_add_f32_e32 v95, 1.0, v95
	v_rcp_f32_e32 v97, v95
	s_nop 0
	v_fma_f32 v99, -v95, v97, 1.0
	v_fma_f32 v96, v99, v97, v97
	v_div_fixup_f32 v95, v96, v95, 1.0
	v_mul_f32_e32 v95, 0xbf1b459e, v95
	v_mul_f32_e32 v96, 0x3fb8aa3b, v95
	v_exp_f32_e32 v96, v96
	s_nop 0
	v_sub_f32_e32 v95, 1.0, v96

; __device__ __forceinline__ float sigmoidf_(float x) { return 1.0f / (1.0f + __expf(-x)); }
;     __device__ __forceinline__ void operator()(const f32x4 (&acc)[2][2][4][2], const Unit& u, int wr, int wc, int fr, int fq) const {
;     ...
;                         for (int i = 0; i < 4; ++i) { float xv = acc[ai][bj][m][n][i] + bv[bj][n][i]; float r;
;                             if (type < 2) { const float sg = sigmoidf_(xv); r = -expm1f(-0.606531f * sg); }
;                             else if (type == 2) r = sigmoidf_(xv);
;                             else r = xv;
;                             v[4 * n + i] = (f16)r; }
.LBB0_785:
	v_mul_f32_e32 v88, 0xbfb8aa3b, v88
	v_exp_f32_e32 v88, v88
	s_nop 0
	v_add_f32_e32 v88, 1.0, v88
	v_rcp_f32_e32 v97, v88
	s_nop 0
	v_fma_f32 v99, -v88, v97, 1.0
	v_fma_f32 v96, v99, v97, v97
	v_div_fixup_f32 v88, v96, v88, 1.0
	v_mul_f32_e32 v88, 0xbf1b459e, v88
	v_mul_f32_e32 v96, 0x3fb8aa3b, v88
	v_exp_f32_e32 v96, v96
	s_nop 0
	v_sub_f32_e32 v96, 1.0, v96

; __device__ __forceinline__ float sigmoidf_(float x) { return 1.0f / (1.0f + __expf(-x)); }
;     __device__ __forceinline__ void operator()(const f32x4 (&acc)[2][2][4][2], const Unit& u, int wr, int wc, int fr, int fq) const {
;     ...
;                         for (int i = 0; i < 4; ++i) { float xv = acc[ai][bj][m][n][i] + bv[bj][n][i]; float r;
;                             if (type < 2) { const float sg = sigmoidf_(xv); r = -expm1f(-0.606531f * sg); }
;                             else if (type == 2) r = sigmoidf_(xv);
;                             else r = xv;
;                             v[4 * n + i] = (f16)r; }
.LBB0_791:
	v_mul_f32_e32 v88, 0xbfb8aa3b, v88
	v_exp_f32_e32 v88, v88
	s_nop 0
	v_add_f32_e32 v88, 1.0, v88
	v_rcp_f32_e32 v97, v88
	s_nop 0
	v_fma_f32 v99, -v88, v97, 1.0
	v_fma_f32 v89, v99, v97, v97
	v_div_fixup_f32 v88, v89, v88, 1.0
	v_mul_f32_e32 v88, 0xbf1b459e, v88
	v_mul_f32_e32 v89, 0x3fb8aa3b, v88
	v_exp_f32_e32 v89, v89
	s_nop 0
	v_sub_f32_e32 v97, 1.0, v89

; __device__ __forceinline__ float sigmoidf_(float x) { return 1.0f / (1.0f + __expf(-x)); }
;     __device__ __forceinline__ void operator()(const f32x4 (&acc)[2][2][4][2], const Unit& u, int wr, int wc, int fr, int fq) const {
;     ...
;                         for (int i = 0; i < 4; ++i) { float xv = acc[ai][bj][m][n][i] + bv[bj][n][i]; float r;
;                             if (type < 2) { const float sg = sigmoidf_(xv); r = -expm1f(-0.606531f * sg); }
;                             else if (type == 2) r = sigmoidf_(xv);
;                             else r = xv;
;                             v[4 * n + i] = (f16)r; }
.LBB0_797:
	v_mul_f32_e32 v88, 0xbfb8aa3b, v88
	v_exp_f32_e32 v88, v88
	s_nop 0
	v_add_f32_e32 v88, 1.0, v88
	v_rcp_f32_e32 v90, v88
	s_nop 0
	v_fma_f32 v99, -v88, v90, 1.0
	v_fma_f32 v89, v99, v90, v90
	v_div_fixup_f32 v88, v89, v88, 1.0
	v_mul_f32_e32 v88, 0xbf1b459e, v88
	v_mul_f32_e32 v89, 0x3fb8aa3b, v88
	v_exp_f32_e32 v89, v89
	s_nop 0
	v_sub_f32_e32 v90, 1.0, v89

; __device__ __forceinline__ float sigmoidf_(float x) { return 1.0f / (1.0f + __expf(-x)); }
;     __device__ __forceinline__ void operator()(const f32x4 (&acc)[2][2][4][2], const Unit& u, int wr, int wc, int fr, int fq) const {
;     ...
;                         for (int i = 0; i < 4; ++i) { float xv = acc[ai][bj][m][n][i] + bv[bj][n][i]; float r;
;                             if (type < 2) { const float sg = sigmoidf_(xv); r = -expm1f(-0.606531f * sg); }
.LBB0_803:
	v_mul_f32_e32 v88, 0xbfb8aa3b, v88
	v_exp_f32_e32 v88, v88
	s_nop 0
	v_add_f32_e32 v88, 1.0, v88
	v_rcp_f32_e32 v91, v88
	s_nop 0
	v_fma_f32 v99, -v88, v91, 1.0
	v_fma_f32 v89, v99, v91, v91
	v_div_fixup_f32 v88, v89, v88, 1.0
	v_mul_f32_e32 v88, 0xbf1b459e, v88
	v_mul_f32_e32 v89, 0x3fb8aa3b, v88
	v_exp_f32_e32 v89, v89
	s_nop 0
	v_sub_f32_e32 v91, 1.0, v89

; __device__ __forceinline__ float sigmoidf_(float x) { return 1.0f / (1.0f + __expf(-x)); }
;     __device__ __forceinline__ void operator()(const f32x4 (&acc)[2][2][4][2], const Unit& u, int wr, int wc, int fr, int fq) const {
;     ...
;                         for (int i = 0; i < 4; ++i) { float xv = acc[ai][bj][m][n][i] + bv[bj][n][i]; float r;
;                             if (type < 2) { const float sg = sigmoidf_(xv); r = -expm1f(-0.606531f * sg); }
.LBB0_809:
	v_mul_f32_e32 v84, 0xbfb8aa3b, v90
	v_exp_f32_e32 v84, v84
	s_nop 0
	v_add_f32_e32 v84, 1.0, v84
	v_rcp_f32_e32 v91, v84
	s_nop 0
	v_fma_f32 v93, -v84, v91, 1.0
	v_fma_f32 v90, v93, v91, v91
	v_div_fixup_f32 v84, v90, v84, 1.0
	v_mul_f32_e32 v84, 0xbf1b459e, v84
	v_mul_f32_e32 v90, 0x3fb8aa3b, v84
	v_exp_f32_e32 v90, v90
	s_nop 0
	v_sub_f32_e32 v84, 1.0, v90

; __device__ __forceinline__ float sigmoidf_(float x) { return 1.0f / (1.0f + __expf(-x)); }
;     __device__ __forceinline__ void operator()(const f32x4 (&acc)[2][2][4][2], const Unit& u, int wr, int wc, int fr, int fq) const {
;     ...
;                         for (int i = 0; i < 4; ++i) { float xv = acc[ai][bj][m][n][i] + bv[bj][n][i]; float r;
;                             if (type < 2) { const float sg = sigmoidf_(xv); r = -expm1f(-0.606531f * sg); }
.LBB0_815:
	v_mul_f32_e32 v85, 0xbfb8aa3b, v90
	v_exp_f32_e32 v85, v85
	s_nop 0
	v_add_f32_e32 v85, 1.0, v85
	v_rcp_f32_e32 v91, v85
	s_nop 0
	v_fma_f32 v93, -v85, v91, 1.0
	v_fma_f32 v90, v93, v91, v91
	v_div_fixup_f32 v85, v90, v85, 1.0
	v_mul_f32_e32 v85, 0xbf1b459e, v85
	v_mul_f32_e32 v90, 0x3fb8aa3b, v85
	v_exp_f32_e32 v90, v90
	s_nop 0
	v_sub_f32_e32 v85, 1.0, v90

; __device__ __forceinline__ float sigmoidf_(float x) { return 1.0f / (1.0f + __expf(-x)); }
;     __device__ __forceinline__ void operator()(const f32x4 (&acc)[2][2][4][2], const Unit& u, int wr, int wc, int fr, int fq) const {
;     ...
;                         for (int i = 0; i < 4; ++i) { float xv = acc[ai][bj][m][n][i] + bv[bj][n][i]; float r;
;                             if (type < 2) { const float sg = sigmoidf_(xv); r = -expm1f(-0.606531f * sg); }
.LBB0_821:
	v_mul_f32_e32 v86, 0xbfb8aa3b, v90
	v_exp_f32_e32 v86, v86
	s_nop 0
	v_add_f32_e32 v86, 1.0, v86
	v_rcp_f32_e32 v91, v86
	s_nop 0
	v_fma_f32 v93, -v86, v91, 1.0
	v_fma_f32 v90, v93, v91, v91
	v_div_fixup_f32 v86, v90, v86, 1.0
	v_mul_f32_e32 v86, 0xbf1b459e, v86
	v_mul_f32_e32 v90, 0x3fb8aa3b, v86
	v_exp_f32_e32 v90, v90
	s_nop 0
	v_sub_f32_e32 v86, 1.0, v90

; __device__ __forceinline__ float sigmoidf_(float x) { return 1.0f / (1.0f + __expf(-x)); }
;     __device__ __forceinline__ void operator()(const f32x4 (&acc)[2][2][4][2], const Unit& u, int wr, int wc, int fr, int fq) const {
;     ...
;                         for (int i = 0; i < 4; ++i) { float xv = acc[ai][bj][m][n][i] + bv[bj][n][i]; float r;
;                             if (type < 2) { const float sg = sigmoidf_(xv); r = -expm1f(-0.606531f * sg); }
.LBB0_827:
	v_mul_f32_e32 v87, 0xbfb8aa3b, v90
	v_exp_f32_e32 v87, v87
	s_nop 0
	v_add_f32_e32 v87, 1.0, v87
	v_rcp_f32_e32 v91, v87
	s_nop 0
	v_fma_f32 v93, -v87, v91, 1.0
	v_fma_f32 v90, v93, v91, v91
	v_div_fixup_f32 v87, v90, v87, 1.0
	v_mul_f32_e32 v87, 0xbf1b459e, v87
	v_mul_f32_e32 v90, 0x3fb8aa3b, v87
	v_exp_f32_e32 v90, v90
	s_nop 0
	v_sub_f32_e32 v87, 1.0, v90

; __device__ __forceinline__ float sigmoidf_(float x) { return 1.0f / (1.0f + __expf(-x)); }
;     __device__ __forceinline__ void operator()(const f32x4 (&acc)[2][2][4][2], const Unit& u, int wr, int wc, int fr, int fq) const {
;     ...
;                         for (int i = 0; i < 4; ++i) { float xv = acc[ai][bj][m][n][i] + bv[bj][n][i]; float r;
;                             if (type < 2) { const float sg = sigmoidf_(xv); r = -expm1f(-0.606531f * sg); }
.LBB0_833:
	v_mul_f32_e32 v80, 0xbfb8aa3b, v90
	v_exp_f32_e32 v80, v80
	s_nop 0
	v_add_f32_e32 v80, 1.0, v80
	v_rcp_f32_e32 v91, v80
	s_nop 0
	v_fma_f32 v93, -v80, v91, 1.0
	v_fma_f32 v90, v93, v91, v91
	v_div_fixup_f32 v80, v90, v80, 1.0
	v_mul_f32_e32 v80, 0xbf1b459e, v80
	v_mul_f32_e32 v90, 0x3fb8aa3b, v80
	v_exp_f32_e32 v90, v90
	s_nop 0
	v_sub_f32_e32 v80, 1.0, v90

; __device__ __forceinline__ float sigmoidf_(float x) { return 1.0f / (1.0f + __expf(-x)); }
;     __device__ __forceinline__ void operator()(const f32x4 (&acc)[2][2][4][2], const Unit& u, int wr, int wc, int fr, int fq) const {
;     ...
;                         for (int i = 0; i < 4; ++i) { float xv = acc[ai][bj][m][n][i] + bv[bj][n][i]; float r;
;                             if (type < 2) { const float sg = sigmoidf_(xv); r = -expm1f(-0.606531f * sg); }
.LBB0_839:
	v_mul_f32_e32 v81, 0xbfb8aa3b, v90
	v_exp_f32_e32 v81, v81
	s_nop 0
	v_add_f32_e32 v81, 1.0, v81
	v_rcp_f32_e32 v91, v81
	s_nop 0
	v_fma_f32 v93, -v81, v91, 1.0
	v_fma_f32 v90, v93, v91, v91
	v_div_fixup_f32 v81, v90, v81, 1.0
	v_mul_f32_e32 v81, 0xbf1b459e, v81
	v_mul_f32_e32 v90, 0x3fb8aa3b, v81
	v_exp_f32_e32 v90, v90
	s_nop 0
	v_sub_f32_e32 v81, 1.0, v90

; __device__ __forceinline__ float sigmoidf_(float x) { return 1.0f / (1.0f + __expf(-x)); }
;     __device__ __forceinline__ void operator()(const f32x4 (&acc)[2][2][4][2], const Unit& u, int wr, int wc, int fr, int fq) const {
;     ...
;                         for (int i = 0; i < 4; ++i) { float xv = acc[ai][bj][m][n][i] + bv[bj][n][i]; float r;
;                             if (type < 2) { const float sg = sigmoidf_(xv); r = -expm1f(-0.606531f * sg); }
.LBB0_845:
	v_mul_f32_e32 v82, 0xbfb8aa3b, v90
	v_exp_f32_e32 v82, v82
	s_nop 0
	v_add_f32_e32 v82, 1.0, v82
	v_rcp_f32_e32 v91, v82
	s_nop 0
	v_fma_f32 v93, -v82, v91, 1.0
	v_fma_f32 v90, v93, v91, v91
	v_div_fixup_f32 v82, v90, v82, 1.0
	v_mul_f32_e32 v82, 0xbf1b459e, v82
	v_mul_f32_e32 v90, 0x3fb8aa3b, v82
	v_exp_f32_e32 v90, v90
	s_nop 0
	v_sub_f32_e32 v82, 1.0, v90

; __device__ __forceinline__ float sigmoidf_(float x) { return 1.0f / (1.0f + __expf(-x)); }
;     __device__ __forceinline__ void operator()(const f32x4 (&acc)[2][2][4][2], const Unit& u, int wr, int wc, int fr, int fq) const {
;     ...
;                         for (int i = 0; i < 4; ++i) { float xv = acc[ai][bj][m][n][i] + bv[bj][n][i]; float r;
;                             if (type < 2) { const float sg = sigmoidf_(xv); r = -expm1f(-0.606531f * sg); }
.LBB0_851:
	v_mul_f32_e32 v83, 0xbfb8aa3b, v83
	v_exp_f32_e32 v83, v83
	s_nop 0
	v_add_f32_e32 v83, 1.0, v83
	v_rcp_f32_e32 v91, v83
	s_nop 0
	v_fma_f32 v93, -v83, v91, 1.0
	v_fma_f32 v90, v93, v91, v91
	v_div_fixup_f32 v83, v90, v83, 1.0
	v_mul_f32_e32 v83, 0xbf1b459e, v83
	v_mul_f32_e32 v90, 0x3fb8aa3b, v83
	v_exp_f32_e32 v90, v90
	s_nop 0
	v_sub_f32_e32 v90, 1.0, v90

; __device__ __forceinline__ float sigmoidf_(float x) { return 1.0f / (1.0f + __expf(-x)); }
;     __device__ __forceinline__ void operator()(const f32x4 (&acc)[2][2][4][2], const Unit& u, int wr, int wc, int fr, int fq) const {
;     ...
;                         for (int i = 0; i < 4; ++i) { float xv = acc[ai][bj][m][n][i] + bv[bj][n][i]; float r;
;                             if (type < 2) { const float sg = sigmoidf_(xv); r = -expm1f(-0.606531f * sg); }
.LBB0_857:
	v_mul_f32_e32 v76, 0xbfb8aa3b, v80
	v_exp_f32_e32 v76, v76
	s_nop 0
	v_add_f32_e32 v76, 1.0, v76
	v_rcp_f32_e32 v81, v76
	s_nop 0
	v_fma_f32 v83, -v76, v81, 1.0
	v_fma_f32 v80, v83, v81, v81
	v_div_fixup_f32 v76, v80, v76, 1.0
	v_mul_f32_e32 v76, 0xbf1b459e, v76
	v_mul_f32_e32 v80, 0x3fb8aa3b, v76
	v_exp_f32_e32 v80, v80
	s_nop 0
	v_sub_f32_e32 v76, 1.0, v80

; __device__ __forceinline__ float sigmoidf_(float x) { return 1.0f / (1.0f + __expf(-x)); }
;     __device__ __forceinline__ void operator()(const f32x4 (&acc)[2][2][4][2], const Unit& u, int wr, int wc, int fr, int fq) const {
;     ...
;                         for (int i = 0; i < 4; ++i) { float xv = acc[ai][bj][m][n][i] + bv[bj][n][i]; float r;
;                             if (type < 2) { const float sg = sigmoidf_(xv); r = -expm1f(-0.606531f * sg); }
.LBB0_863:
	v_mul_f32_e32 v77, 0xbfb8aa3b, v80
	v_exp_f32_e32 v77, v77
	s_nop 0
	v_add_f32_e32 v77, 1.0, v77
	v_rcp_f32_e32 v81, v77
	s_nop 0
	v_fma_f32 v83, -v77, v81, 1.0
	v_fma_f32 v80, v83, v81, v81
	v_div_fixup_f32 v77, v80, v77, 1.0
	v_mul_f32_e32 v77, 0xbf1b459e, v77
	v_mul_f32_e32 v80, 0x3fb8aa3b, v77
	v_exp_f32_e32 v80, v80
	s_nop 0
	v_sub_f32_e32 v77, 1.0, v80

; __device__ __forceinline__ float sigmoidf_(float x) { return 1.0f / (1.0f + __expf(-x)); }
;     __device__ __forceinline__ void operator()(const f32x4 (&acc)[2][2][4][2], const Unit& u, int wr, int wc, int fr, int fq) const {
;     ...
;                         for (int i = 0; i < 4; ++i) { float xv = acc[ai][bj][m][n][i] + bv[bj][n][i]; float r;
;                             if (type < 2) { const float sg = sigmoidf_(xv); r = -expm1f(-0.606531f * sg); }
.LBB0_869:
	v_mul_f32_e32 v78, 0xbfb8aa3b, v80
	v_exp_f32_e32 v78, v78
	s_nop 0
	v_add_f32_e32 v78, 1.0, v78
	v_rcp_f32_e32 v81, v78
	s_nop 0
	v_fma_f32 v83, -v78, v81, 1.0
	v_fma_f32 v80, v83, v81, v81
	v_div_fixup_f32 v78, v80, v78, 1.0
	v_mul_f32_e32 v78, 0xbf1b459e, v78
	v_mul_f32_e32 v80, 0x3fb8aa3b, v78
	v_exp_f32_e32 v80, v80
	s_nop 0
	v_sub_f32_e32 v78, 1.0, v80

; __device__ __forceinline__ float sigmoidf_(float x) { return 1.0f / (1.0f + __expf(-x)); }
;     __device__ __forceinline__ void operator()(const f32x4 (&acc)[2][2][4][2], const Unit& u, int wr, int wc, int fr, int fq) const {
;     ...
;                         for (int i = 0; i < 4; ++i) { float xv = acc[ai][bj][m][n][i] + bv[bj][n][i]; float r;
;                             if (type < 2) { const float sg = sigmoidf_(xv); r = -expm1f(-0.606531f * sg); }
.LBB0_875:
	v_mul_f32_e32 v79, 0xbfb8aa3b, v80
	v_exp_f32_e32 v79, v79
	s_nop 0
	v_add_f32_e32 v79, 1.0, v79
	v_rcp_f32_e32 v81, v79
	s_nop 0
	v_fma_f32 v83, -v79, v81, 1.0
	v_fma_f32 v80, v83, v81, v81
	v_div_fixup_f32 v79, v80, v79, 1.0
	v_mul_f32_e32 v79, 0xbf1b459e, v79
	v_mul_f32_e32 v80, 0x3fb8aa3b, v79
	v_exp_f32_e32 v80, v80
	s_nop 0
	v_sub_f32_e32 v79, 1.0, v80

; __device__ __forceinline__ float sigmoidf_(float x) { return 1.0f / (1.0f + __expf(-x)); }
;     __device__ __forceinline__ void operator()(const f32x4 (&acc)[2][2][4][2], const Unit& u, int wr, int wc, int fr, int fq) const {
;     ...
;                         for (int i = 0; i < 4; ++i) { float xv = acc[ai][bj][m][n][i] + bv[bj][n][i]; float r;
;                             if (type < 2) { const float sg = sigmoidf_(xv); r = -expm1f(-0.606531f * sg); }
.LBB0_881:
	v_mul_f32_e32 v72, 0xbfb8aa3b, v72
	v_exp_f32_e32 v72, v72
	s_nop 0
	v_add_f32_e32 v72, 1.0, v72
	v_rcp_f32_e32 v81, v72
	s_nop 0
	v_fma_f32 v83, -v72, v81, 1.0
	v_fma_f32 v80, v83, v81, v81
	v_div_fixup_f32 v72, v80, v72, 1.0
	v_mul_f32_e32 v72, 0xbf1b459e, v72
	v_mul_f32_e32 v80, 0x3fb8aa3b, v72
	v_exp_f32_e32 v80, v80
	s_nop 0
	v_sub_f32_e32 v80, 1.0, v80

; __device__ __forceinline__ float sigmoidf_(float x) { return 1.0f / (1.0f + __expf(-x)); }
;     __device__ __forceinline__ void operator()(const f32x4 (&acc)[2][2][4][2], const Unit& u, int wr, int wc, int fr, int fq) const {
;     ...
;                         for (int i = 0; i < 4; ++i) { float xv = acc[ai][bj][m][n][i] + bv[bj][n][i]; float r;
;                             if (type < 2) { const float sg = sigmoidf_(xv); r = -expm1f(-0.606531f * sg); }
.LBB0_887:
	v_mul_f32_e32 v72, 0xbfb8aa3b, v72
	v_exp_f32_e32 v72, v72
	s_nop 0
	v_add_f32_e32 v72, 1.0, v72
	v_rcp_f32_e32 v81, v72
	s_nop 0
	v_fma_f32 v83, -v72, v81, 1.0
	v_fma_f32 v73, v83, v81, v81
	v_div_fixup_f32 v72, v73, v72, 1.0
	v_mul_f32_e32 v72, 0xbf1b459e, v72
	v_mul_f32_e32 v73, 0x3fb8aa3b, v72
	v_exp_f32_e32 v73, v73
	s_nop 0
	v_sub_f32_e32 v81, 1.0, v73

; __device__ __forceinline__ float sigmoidf_(float x) { return 1.0f / (1.0f + __expf(-x)); }
;     __device__ __forceinline__ void operator()(const f32x4 (&acc)[2][2][4][2], const Unit& u, int wr, int wc, int fr, int fq) const {
;     ...
;                         for (int i = 0; i < 4; ++i) { float xv = acc[ai][bj][m][n][i] + bv[bj][n][i]; float r;
;                             if (type < 2) { const float sg = sigmoidf_(xv); r = -expm1f(-0.606531f * sg); }
.LBB0_893:
	v_mul_f32_e32 v72, 0xbfb8aa3b, v72
	v_exp_f32_e32 v72, v72
	s_nop 0
	v_add_f32_e32 v72, 1.0, v72
	v_rcp_f32_e32 v74, v72
	s_nop 0
	v_fma_f32 v83, -v72, v74, 1.0
	v_fma_f32 v73, v83, v74, v74
	v_div_fixup_f32 v72, v73, v72, 1.0
	v_mul_f32_e32 v72, 0xbf1b459e, v72
	v_mul_f32_e32 v73, 0x3fb8aa3b, v72
	v_exp_f32_e32 v73, v73
	s_nop 0
	v_sub_f32_e32 v74, 1.0, v73

; __device__ __forceinline__ float sigmoidf_(float x) { return 1.0f / (1.0f + __expf(-x)); }
;     __device__ __forceinline__ void operator()(const f32x4 (&acc)[2][2][4][2], const Unit& u, int wr, int wc, int fr, int fq) const {
;     ...
;                         for (int i = 0; i < 4; ++i) { float xv = acc[ai][bj][m][n][i] + bv[bj][n][i]; float r;
;                             if (type < 2) { const float sg = sigmoidf_(xv); r = -expm1f(-0.606531f * sg); }
.LBB0_899:
	v_mul_f32_e32 v72, 0xbfb8aa3b, v72
	v_exp_f32_e32 v72, v72
	s_nop 0
	v_add_f32_e32 v72, 1.0, v72
	v_rcp_f32_e32 v75, v72
	s_nop 0
	v_fma_f32 v83, -v72, v75, 1.0
	v_fma_f32 v73, v83, v75, v75
	v_div_fixup_f32 v72, v73, v72, 1.0
	v_mul_f32_e32 v72, 0xbf1b459e, v72
	v_mul_f32_e32 v73, 0x3fb8aa3b, v72
	v_exp_f32_e32 v73, v73
	s_nop 0
	v_sub_f32_e32 v75, 1.0, v73

; __device__ __forceinline__ float sigmoidf_(float x) { return 1.0f / (1.0f + __expf(-x)); }
;     __device__ __forceinline__ void operator()(const f32x4 (&acc)[2][2][4][2], const Unit& u, int wr, int wc, int fr, int fq) const {
;     ...
;                         for (int i = 0; i < 4; ++i) { float xv = acc[ai][bj][m][n][i] + bv[bj][n][i]; float r;
;                             if (type < 2) { const float sg = sigmoidf_(xv); r = -expm1f(-0.606531f * sg); }
.LBB0_905:
	v_mul_f32_e32 v68, 0xbfb8aa3b, v74
	v_exp_f32_e32 v68, v68
	s_nop 0
	v_add_f32_e32 v68, 1.0, v68
	v_rcp_f32_e32 v75, v68
	s_nop 0
	v_fma_f32 v77, -v68, v75, 1.0
	v_fma_f32 v74, v77, v75, v75
	v_div_fixup_f32 v68, v74, v68, 1.0
	v_mul_f32_e32 v68, 0xbf1b459e, v68
	v_mul_f32_e32 v74, 0x3fb8aa3b, v68
	v_exp_f32_e32 v74, v74
	s_nop 0
	v_sub_f32_e32 v68, 1.0, v74

; __device__ __forceinline__ float sigmoidf_(float x) { return 1.0f / (1.0f + __expf(-x)); }
;     __device__ __forceinline__ void operator()(const f32x4 (&acc)[2][2][4][2], const Unit& u, int wr, int wc, int fr, int fq) const {
;     ...
;                         for (int i = 0; i < 4; ++i) { float xv = acc[ai][bj][m][n][i] + bv[bj][n][i]; float r;
;                             if (type < 2) { const float sg = sigmoidf_(xv); r = -expm1f(-0.606531f * sg); }
.LBB0_911:
	v_mul_f32_e32 v69, 0xbfb8aa3b, v74
	v_exp_f32_e32 v69, v69
	s_nop 0
	v_add_f32_e32 v69, 1.0, v69
	v_rcp_f32_e32 v75, v69
	s_nop 0
	v_fma_f32 v77, -v69, v75, 1.0
	v_fma_f32 v74, v77, v75, v75
	v_div_fixup_f32 v69, v74, v69, 1.0
	v_mul_f32_e32 v69, 0xbf1b459e, v69
	v_mul_f32_e32 v74, 0x3fb8aa3b, v69
	v_exp_f32_e32 v74, v74
	s_nop 0
	v_sub_f32_e32 v69, 1.0, v74

; __device__ __forceinline__ float sigmoidf_(float x) { return 1.0f / (1.0f + __expf(-x)); }
;     __device__ __forceinline__ void operator()(const f32x4 (&acc)[2][2][4][2], const Unit& u, int wr, int wc, int fr, int fq) const {
;     ...
;                         for (int i = 0; i < 4; ++i) { float xv = acc[ai][bj][m][n][i] + bv[bj][n][i]; float r;
;                             if (type < 2) { const float sg = sigmoidf_(xv); r = -expm1f(-0.606531f * sg); }
.LBB0_917:
	v_mul_f32_e32 v70, 0xbfb8aa3b, v74
	v_exp_f32_e32 v70, v70
	s_nop 0
	v_add_f32_e32 v70, 1.0, v70
	v_rcp_f32_e32 v75, v70
	s_nop 0
	v_fma_f32 v77, -v70, v75, 1.0
	v_fma_f32 v74, v77, v75, v75
	v_div_fixup_f32 v70, v74, v70, 1.0
	v_mul_f32_e32 v70, 0xbf1b459e, v70
	v_mul_f32_e32 v74, 0x3fb8aa3b, v70
	v_exp_f32_e32 v74, v74
	s_nop 0
	v_sub_f32_e32 v70, 1.0, v74

; __device__ __forceinline__ float sigmoidf_(float x) { return 1.0f / (1.0f + __expf(-x)); }
;     __device__ __forceinline__ void operator()(const f32x4 (&acc)[2][2][4][2], const Unit& u, int wr, int wc, int fr, int fq) const {
;     ...
;                         for (int i = 0; i < 4; ++i) { float xv = acc[ai][bj][m][n][i] + bv[bj][n][i]; float r;
;                             if (type < 2) { const float sg = sigmoidf_(xv); r = -expm1f(-0.606531f * sg); }
.LBB0_923:
	v_mul_f32_e32 v71, 0xbfb8aa3b, v74
	v_exp_f32_e32 v71, v71
	s_nop 0
	v_add_f32_e32 v71, 1.0, v71
	v_rcp_f32_e32 v75, v71
	s_nop 0
	v_fma_f32 v77, -v71, v75, 1.0
	v_fma_f32 v74, v77, v75, v75
	v_div_fixup_f32 v71, v74, v71, 1.0
	v_mul_f32_e32 v71, 0xbf1b459e, v71
	v_mul_f32_e32 v74, 0x3fb8aa3b, v71
	v_exp_f32_e32 v74, v74
	s_nop 0
	v_sub_f32_e32 v71, 1.0, v74

; __device__ __forceinline__ float sigmoidf_(float x) { return 1.0f / (1.0f + __expf(-x)); }
;     __device__ __forceinline__ void operator()(const f32x4 (&acc)[2][2][4][2], const Unit& u, int wr, int wc, int fr, int fq) const {
;     ...
;                         for (int i = 0; i < 4; ++i) { float xv = acc[ai][bj][m][n][i] + bv[bj][n][i]; float r;
;                             if (type < 2) { const float sg = sigmoidf_(xv); r = -expm1f(-0.606531f * sg); }
.LBB0_929:
	v_mul_f32_e32 v64, 0xbfb8aa3b, v74
	v_exp_f32_e32 v64, v64
	s_nop 0
	v_add_f32_e32 v64, 1.0, v64
	v_rcp_f32_e32 v75, v64
	s_nop 0
	v_fma_f32 v77, -v64, v75, 1.0
	v_fma_f32 v74, v77, v75, v75
	v_div_fixup_f32 v64, v74, v64, 1.0
	v_mul_f32_e32 v64, 0xbf1b459e, v64
	v_mul_f32_e32 v74, 0x3fb8aa3b, v64
	v_exp_f32_e32 v74, v74
	s_nop 0
	v_sub_f32_e32 v64, 1.0, v74

; __device__ __forceinline__ float sigmoidf_(float x) { return 1.0f / (1.0f + __expf(-x)); }
;     __device__ __forceinline__ void operator()(const f32x4 (&acc)[2][2][4][2], const Unit& u, int wr, int wc, int fr, int fq) const {
;     ...
;                         for (int i = 0; i < 4; ++i) { float xv = acc[ai][bj][m][n][i] + bv[bj][n][i]; float r;
;                             if (type < 2) { const float sg = sigmoidf_(xv); r = -expm1f(-0.606531f * sg); }
.LBB0_935:
	v_mul_f32_e32 v65, 0xbfb8aa3b, v74
	v_exp_f32_e32 v65, v65
	s_nop 0
	v_add_f32_e32 v65, 1.0, v65
	v_rcp_f32_e32 v75, v65
	s_nop 0
	v_fma_f32 v77, -v65, v75, 1.0
	v_fma_f32 v74, v77, v75, v75
	v_div_fixup_f32 v65, v74, v65, 1.0
	v_mul_f32_e32 v65, 0xbf1b459e, v65
	v_mul_f32_e32 v74, 0x3fb8aa3b, v65
	v_exp_f32_e32 v74, v74
	s_nop 0
	v_sub_f32_e32 v65, 1.0, v74

; __device__ __forceinline__ float sigmoidf_(float x) { return 1.0f / (1.0f + __expf(-x)); }
;     __device__ __forceinline__ void operator()(const f32x4 (&acc)[2][2][4][2], const Unit& u, int wr, int wc, int fr, int fq) const {
;     ...
;                         for (int i = 0; i < 4; ++i) { float xv = acc[ai][bj][m][n][i] + bv[bj][n][i]; float r;
;                             if (type < 2) { const float sg = sigmoidf_(xv); r = -expm1f(-0.606531f * sg); }
.LBB0_941:
	v_mul_f32_e32 v66, 0xbfb8aa3b, v74
	v_exp_f32_e32 v66, v66
	s_nop 0
	v_add_f32_e32 v66, 1.0, v66
	v_rcp_f32_e32 v75, v66
	s_nop 0
	v_fma_f32 v77, -v66, v75, 1.0
	v_fma_f32 v74, v77, v75, v75
	v_div_fixup_f32 v66, v74, v66, 1.0
	v_mul_f32_e32 v66, 0xbf1b459e, v66
	v_mul_f32_e32 v74, 0x3fb8aa3b, v66
	v_exp_f32_e32 v74, v74
	s_nop 0
	v_sub_f32_e32 v66, 1.0, v74

; __device__ __forceinline__ float sigmoidf_(float x) { return 1.0f / (1.0f + __expf(-x)); }
;     __device__ __forceinline__ void operator()(const f32x4 (&acc)[2][2][4][2], const Unit& u, int wr, int wc, int fr, int fq) const {
;     ...
;                         for (int i = 0; i < 4; ++i) { float xv = acc[ai][bj][m][n][i] + bv[bj][n][i]; float r;
;                             if (type < 2) { const float sg = sigmoidf_(xv); r = -expm1f(-0.606531f * sg); }
.LBB0_947:
	v_mul_f32_e32 v67, 0xbfb8aa3b, v67
	v_exp_f32_e32 v67, v67
	s_nop 0
	v_add_f32_e32 v67, 1.0, v67
	v_rcp_f32_e32 v75, v67
	s_nop 0
	v_fma_f32 v77, -v67, v75, 1.0
	v_fma_f32 v74, v77, v75, v75
	v_div_fixup_f32 v67, v74, v67, 1.0
	v_mul_f32_e32 v67, 0xbf1b459e, v67
	v_mul_f32_e32 v74, 0x3fb8aa3b, v67
	v_exp_f32_e32 v74, v74
	s_nop 0
	v_sub_f32_e32 v74, 1.0, v74

; __device__ __forceinline__ float sigmoidf_(float x) { return 1.0f / (1.0f + __expf(-x)); }
;     __device__ __forceinline__ void operator()(const f32x4 (&acc)[2][2][4][2], const Unit& u, int wr, int wc, int fr, int fq) const {
;     ...
;                         for (int i = 0; i < 4; ++i) { float xv = acc[ai][bj][m][n][i] + bv[bj][n][i]; float r;
;                             if (type < 2) { const float sg = sigmoidf_(xv); r = -expm1f(-0.606531f * sg); }
.LBB0_953:
	v_mul_f32_e32 v60, 0xbfb8aa3b, v64
	v_exp_f32_e32 v60, v60
	s_nop 0
	v_add_f32_e32 v60, 1.0, v60
	v_rcp_f32_e32 v65, v60
	s_nop 0
	v_fma_f32 v67, -v60, v65, 1.0
	v_fma_f32 v64, v67, v65, v65
	v_div_fixup_f32 v60, v64, v60, 1.0
	v_mul_f32_e32 v60, 0xbf1b459e, v60
	v_mul_f32_e32 v64, 0x3fb8aa3b, v60
	v_exp_f32_e32 v64, v64
	s_nop 0
	v_sub_f32_e32 v60, 1.0, v64

; __device__ __forceinline__ float sigmoidf_(float x) { return 1.0f / (1.0f + __expf(-x)); }
;     __device__ __forceinline__ void operator()(const f32x4 (&acc)[2][2][4][2], const Unit& u, int wr, int wc, int fr, int fq) const {
;     ...
;                         for (int i = 0; i < 4; ++i) { float xv = acc[ai][bj][m][n][i] + bv[bj][n][i]; float r;
;                             if (type < 2) { const float sg = sigmoidf_(xv); r = -expm1f(-0.606531f * sg); }
.LBB0_959:
	v_mul_f32_e32 v61, 0xbfb8aa3b, v64
	v_exp_f32_e32 v61, v61
	s_nop 0
	v_add_f32_e32 v61, 1.0, v61
	v_rcp_f32_e32 v65, v61
	s_nop 0
	v_fma_f32 v67, -v61, v65, 1.0
	v_fma_f32 v64, v67, v65, v65
	v_div_fixup_f32 v61, v64, v61, 1.0
	v_mul_f32_e32 v61, 0xbf1b459e, v61
	v_mul_f32_e32 v64, 0x3fb8aa3b, v61
	v_exp_f32_e32 v64, v64
	s_nop 0
	v_sub_f32_e32 v61, 1.0, v64

; __device__ __forceinline__ float sigmoidf_(float x) { return 1.0f / (1.0f + __expf(-x)); }
;     __device__ __forceinline__ void operator()(const f32x4 (&acc)[2][2][4][2], const Unit& u, int wr, int wc, int fr, int fq) const {
;     ...
;                         for (int i = 0; i < 4; ++i) { float xv = acc[ai][bj][m][n][i] + bv[bj][n][i]; float r;
;                             if (type < 2) { const float sg = sigmoidf_(xv); r = -expm1f(-0.606531f * sg); }
.LBB0_965:
	v_mul_f32_e32 v62, 0xbfb8aa3b, v64
	v_exp_f32_e32 v62, v62
	s_nop 0
	v_add_f32_e32 v62, 1.0, v62
	v_rcp_f32_e32 v65, v62
	s_nop 0
	v_fma_f32 v67, -v62, v65, 1.0
	v_fma_f32 v64, v67, v65, v65
	v_div_fixup_f32 v62, v64, v62, 1.0
	v_mul_f32_e32 v62, 0xbf1b459e, v62
	v_mul_f32_e32 v64, 0x3fb8aa3b, v62
	v_exp_f32_e32 v64, v64
	s_nop 0
	v_sub_f32_e32 v62, 1.0, v64

; __device__ __forceinline__ float sigmoidf_(float x) { return 1.0f / (1.0f + __expf(-x)); }
;     __device__ __forceinline__ void operator()(const f32x4 (&acc)[2][2][4][2], const Unit& u, int wr, int wc, int fr, int fq) const {
;     ...
;                         for (int i = 0; i < 4; ++i) { float xv = acc[ai][bj][m][n][i] + bv[bj][n][i]; float r;
;                             if (type < 2) { const float sg = sigmoidf_(xv); r = -expm1f(-0.606531f * sg); }
.LBB0_971:
	v_mul_f32_e32 v63, 0xbfb8aa3b, v64
	v_exp_f32_e32 v63, v63
	s_nop 0
	v_add_f32_e32 v63, 1.0, v63
	v_rcp_f32_e32 v65, v63
	s_nop 0
	v_fma_f32 v67, -v63, v65, 1.0
	v_fma_f32 v64, v67, v65, v65
	v_div_fixup_f32 v63, v64, v63, 1.0
	v_mul_f32_e32 v63, 0xbf1b459e, v63
	v_mul_f32_e32 v64, 0x3fb8aa3b, v63
	v_exp_f32_e32 v64, v64
	s_nop 0
	v_sub_f32_e32 v63, 1.0, v64

; __device__ __forceinline__ float sigmoidf_(float x) { return 1.0f / (1.0f + __expf(-x)); }
;     __device__ __forceinline__ void operator()(const f32x4 (&acc)[2][2][4][2], const Unit& u, int wr, int wc, int fr, int fq) const {
;     ...
;                         for (int i = 0; i < 4; ++i) { float xv = acc[ai][bj][m][n][i] + bv[bj][n][i]; float r;
;                             if (type < 2) { const float sg = sigmoidf_(xv); r = -expm1f(-0.606531f * sg); }
.LBB0_977:
	v_mul_f32_e32 v56, 0xbfb8aa3b, v56
	v_exp_f32_e32 v56, v56
	s_nop 0
	v_add_f32_e32 v56, 1.0, v56
	v_rcp_f32_e32 v65, v56
	s_nop 0
	v_fma_f32 v67, -v56, v65, 1.0
	v_fma_f32 v64, v67, v65, v65
	v_div_fixup_f32 v56, v64, v56, 1.0
	v_mul_f32_e32 v56, 0xbf1b459e, v56
	v_mul_f32_e32 v64, 0x3fb8aa3b, v56
	v_exp_f32_e32 v64, v64
	s_nop 0
	v_sub_f32_e32 v64, 1.0, v64

; __device__ __forceinline__ float sigmoidf_(float x) { return 1.0f / (1.0f + __expf(-x)); }
;     __device__ __forceinline__ void operator()(const f32x4 (&acc)[2][2][4][2], const Unit& u, int wr, int wc, int fr, int fq) const {
;     ...
;                         for (int i = 0; i < 4; ++i) { float xv = acc[ai][bj][m][n][i] + bv[bj][n][i]; float r;
;                             if (type < 2) { const float sg = sigmoidf_(xv); r = -expm1f(-0.606531f * sg); }
.LBB0_983:
	v_mul_f32_e32 v56, 0xbfb8aa3b, v56
	v_exp_f32_e32 v56, v56
	s_nop 0
	v_add_f32_e32 v56, 1.0, v56
	v_rcp_f32_e32 v65, v56
	s_nop 0
	v_fma_f32 v67, -v56, v65, 1.0
	v_fma_f32 v57, v67, v65, v65
	v_div_fixup_f32 v56, v57, v56, 1.0
	v_mul_f32_e32 v56, 0xbf1b459e, v56
	v_mul_f32_e32 v57, 0x3fb8aa3b, v56
	v_exp_f32_e32 v57, v57
	s_nop 0
	v_sub_f32_e32 v65, 1.0, v57

; __device__ __forceinline__ float sigmoidf_(float x) { return 1.0f / (1.0f + __expf(-x)); }
;     __device__ __forceinline__ void operator()(const f32x4 (&acc)[2][2][4][2], const Unit& u, int wr, int wc, int fr, int fq) const {
;     ...
;                         for (int i = 0; i < 4; ++i) { float xv = acc[ai][bj][m][n][i] + bv[bj][n][i]; float r;
;                             if (type < 2) { const float sg = sigmoidf_(xv); r = -expm1f(-0.606531f * sg); }
.LBB0_989:
	v_mul_f32_e32 v56, 0xbfb8aa3b, v56
	v_exp_f32_e32 v56, v56
	s_nop 0
	v_add_f32_e32 v56, 1.0, v56
	v_rcp_f32_e32 v58, v56
	s_nop 0
	v_fma_f32 v67, -v56, v58, 1.0
	v_fma_f32 v57, v67, v58, v58
	v_div_fixup_f32 v56, v57, v56, 1.0
	v_mul_f32_e32 v56, 0xbf1b459e, v56
	v_mul_f32_e32 v57, 0x3fb8aa3b, v56
	v_exp_f32_e32 v57, v57
	s_nop 0
	v_sub_f32_e32 v58, 1.0, v57

; __device__ __forceinline__ float sigmoidf_(float x) { return 1.0f / (1.0f + __expf(-x)); }
;     __device__ __forceinline__ void operator()(const f32x4 (&acc)[2][2][4][2], const Unit& u, int wr, int wc, int fr, int fq) const {
;     ...
;                         for (int i = 0; i < 4; ++i) { float xv = acc[ai][bj][m][n][i] + bv[bj][n][i]; float r;
;                             if (type < 2) { const float sg = sigmoidf_(xv); r = -expm1f(-0.606531f * sg); }
.LBB0_995:
	v_mul_f32_e32 v56, 0xbfb8aa3b, v56
	v_exp_f32_e32 v56, v56
	s_nop 0
	v_add_f32_e32 v56, 1.0, v56
	v_rcp_f32_e32 v59, v56
	s_nop 0
	v_fma_f32 v67, -v56, v59, 1.0
	v_fma_f32 v57, v67, v59, v59
	v_div_fixup_f32 v56, v57, v56, 1.0
	v_mul_f32_e32 v56, 0xbf1b459e, v56
	v_mul_f32_e32 v57, 0x3fb8aa3b, v56
	v_exp_f32_e32 v57, v57
	s_nop 0
	v_sub_f32_e32 v59, 1.0, v57

; __device__ __forceinline__ float sigmoidf_(float x) { return 1.0f / (1.0f + __expf(-x)); }
;     __device__ __forceinline__ void operator()(const f32x4 (&acc)[2][2][4][2], const Unit& u, int wr, int wc, int fr, int fq) const {
;     ...
;                         for (int i = 0; i < 4; ++i) { float xv = acc[ai][bj][m][n][i] + bv[bj][n][i]; float r;
;                             if (type < 2) { const float sg = sigmoidf_(xv); r = -expm1f(-0.606531f * sg); }
.LBB0_1001:
	v_mul_f32_e32 v52, 0xbfb8aa3b, v58
	v_exp_f32_e32 v52, v52
	s_nop 0
	v_add_f32_e32 v52, 1.0, v52
	v_rcp_f32_e32 v59, v52
	s_nop 0
	v_fma_f32 v61, -v52, v59, 1.0
	v_fma_f32 v58, v61, v59, v59
	v_div_fixup_f32 v52, v58, v52, 1.0
	v_mul_f32_e32 v52, 0xbf1b459e, v52
	v_mul_f32_e32 v58, 0x3fb8aa3b, v52
	v_exp_f32_e32 v58, v58
	s_nop 0
	v_sub_f32_e32 v52, 1.0, v58

; __device__ __forceinline__ float sigmoidf_(float x) { return 1.0f / (1.0f + __expf(-x)); }
;     __device__ __forceinline__ void operator()(const f32x4 (&acc)[2][2][4][2], const Unit& u, int wr, int wc, int fr, int fq) const {
;     ...
;                         for (int i = 0; i < 4; ++i) { float xv = acc[ai][bj][m][n][i] + bv[bj][n][i]; float r;
;                             if (type < 2) { const float sg = sigmoidf_(xv); r = -expm1f(-0.606531f * sg); }
.LBB0_1007:
	v_mul_f32_e32 v53, 0xbfb8aa3b, v58
	v_exp_f32_e32 v53, v53
	s_nop 0
	v_add_f32_e32 v53, 1.0, v53
	v_rcp_f32_e32 v59, v53
	s_nop 0
	v_fma_f32 v61, -v53, v59, 1.0
	v_fma_f32 v58, v61, v59, v59
	v_div_fixup_f32 v53, v58, v53, 1.0
	v_mul_f32_e32 v53, 0xbf1b459e, v53
	v_mul_f32_e32 v58, 0x3fb8aa3b, v53
	v_exp_f32_e32 v58, v58
	s_nop 0
	v_sub_f32_e32 v53, 1.0, v58

; __device__ __forceinline__ float sigmoidf_(float x) { return 1.0f / (1.0f + __expf(-x)); }
;     __device__ __forceinline__ void operator()(const f32x4 (&acc)[2][2][4][2], const Unit& u, int wr, int wc, int fr, int fq) const {
;     ...
;                         for (int i = 0; i < 4; ++i) { float xv = acc[ai][bj][m][n][i] + bv[bj][n][i]; float r;
;                             if (type < 2) { const float sg = sigmoidf_(xv); r = -expm1f(-0.606531f * sg); }
.LBB0_1013:
	v_mul_f32_e32 v54, 0xbfb8aa3b, v58
	v_exp_f32_e32 v54, v54
	s_nop 0
	v_add_f32_e32 v54, 1.0, v54
	v_rcp_f32_e32 v59, v54
	s_nop 0
	v_fma_f32 v61, -v54, v59, 1.0
	v_fma_f32 v58, v61, v59, v59
	v_div_fixup_f32 v54, v58, v54, 1.0
	v_mul_f32_e32 v54, 0xbf1b459e, v54
	v_mul_f32_e32 v58, 0x3fb8aa3b, v54
	v_exp_f32_e32 v58, v58
	s_nop 0
	v_sub_f32_e32 v54, 1.0, v58

; __device__ __forceinline__ float sigmoidf_(float x) { return 1.0f / (1.0f + __expf(-x)); }
;     __device__ __forceinline__ void operator()(const f32x4 (&acc)[2][2][4][2], const Unit& u, int wr, int wc, int fr, int fq) const {
;     ...
;                         for (int i = 0; i < 4; ++i) { float xv = acc[ai][bj][m][n][i] + bv[bj][n][i]; float r;
;                             if (type < 2) { const float sg = sigmoidf_(xv); r = -expm1f(-0.606531f * sg); }
.LBB0_1019:
	v_mul_f32_e32 v55, 0xbfb8aa3b, v58
	v_exp_f32_e32 v55, v55
	s_nop 0
	v_add_f32_e32 v55, 1.0, v55
	v_rcp_f32_e32 v59, v55
	s_nop 0
	v_fma_f32 v61, -v55, v59, 1.0
	v_fma_f32 v58, v61, v59, v59
	v_div_fixup_f32 v55, v58, v55, 1.0
	v_mul_f32_e32 v55, 0xbf1b459e, v55
	v_mul_f32_e32 v58, 0x3fb8aa3b, v55
	v_exp_f32_e32 v58, v58
	s_nop 0
	v_sub_f32_e32 v55, 1.0, v58

; __device__ __forceinline__ float sigmoidf_(float x) { return 1.0f / (1.0f + __expf(-x)); }
;     __device__ __forceinline__ void operator()(const f32x4 (&acc)[2][2][4][2], const Unit& u, int wr, int wc, int fr, int fq) const {
;     ...
;                         for (int i = 0; i < 4; ++i) { float xv = acc[ai][bj][m][n][i] + bv[bj][n][i]; float r;
;                             if (type < 2) { const float sg = sigmoidf_(xv); r = -expm1f(-0.606531f * sg); }
.LBB0_1025:
	v_mul_f32_e32 v48, 0xbfb8aa3b, v58
	v_exp_f32_e32 v48, v48
	s_nop 0
	v_add_f32_e32 v48, 1.0, v48
	v_rcp_f32_e32 v59, v48
	s_nop 0
	v_fma_f32 v61, -v48, v59, 1.0
	v_fma_f32 v58, v61, v59, v59
	v_div_fixup_f32 v48, v58, v48, 1.0
	v_mul_f32_e32 v48, 0xbf1b459e, v48
	v_mul_f32_e32 v58, 0x3fb8aa3b, v48
	v_exp_f32_e32 v58, v58
	s_nop 0
	v_sub_f32_e32 v48, 1.0, v58

; __device__ __forceinline__ float sigmoidf_(float x) { return 1.0f / (1.0f + __expf(-x)); }
;     __device__ __forceinline__ void operator()(const f32x4 (&acc)[2][2][4][2], const Unit& u, int wr, int wc, int fr, int fq) const {
;     ...
;                         for (int i = 0; i < 4; ++i) { float xv = acc[ai][bj][m][n][i] + bv[bj][n][i]; float r;
;                             if (type < 2) { const float sg = sigmoidf_(xv); r = -expm1f(-0.606531f * sg); }
.LBB0_1031:
	v_mul_f32_e32 v49, 0xbfb8aa3b, v58
	v_exp_f32_e32 v49, v49
	s_nop 0
	v_add_f32_e32 v49, 1.0, v49
	v_rcp_f32_e32 v59, v49
	s_nop 0
	v_fma_f32 v61, -v49, v59, 1.0
	v_fma_f32 v58, v61, v59, v59
	v_div_fixup_f32 v49, v58, v49, 1.0
	v_mul_f32_e32 v49, 0xbf1b459e, v49
	v_mul_f32_e32 v58, 0x3fb8aa3b, v49
	v_exp_f32_e32 v58, v58
	s_nop 0
	v_sub_f32_e32 v49, 1.0, v58

; __device__ __forceinline__ float sigmoidf_(float x) { return 1.0f / (1.0f + __expf(-x)); }
;     __device__ __forceinline__ void operator()(const f32x4 (&acc)[2][2][4][2], const Unit& u, int wr, int wc, int fr, int fq) const {
;     ...
;                         for (int i = 0; i < 4; ++i) { float xv = acc[ai][bj][m][n][i] + bv[bj][n][i]; float r;
;                             if (type < 2) { const float sg = sigmoidf_(xv); r = -expm1f(-0.606531f * sg); }
.LBB0_1037:
	v_mul_f32_e32 v50, 0xbfb8aa3b, v58
	v_exp_f32_e32 v50, v50
	s_nop 0
	v_add_f32_e32 v50, 1.0, v50
	v_rcp_f32_e32 v59, v50
	s_nop 0
	v_fma_f32 v61, -v50, v59, 1.0
	v_fma_f32 v58, v61, v59, v59
	v_div_fixup_f32 v50, v58, v50, 1.0
	v_mul_f32_e32 v50, 0xbf1b459e, v50
	v_mul_f32_e32 v58, 0x3fb8aa3b, v50
	v_exp_f32_e32 v58, v58
	s_nop 0
	v_sub_f32_e32 v50, 1.0, v58

; __device__ __forceinline__ float sigmoidf_(float x) { return 1.0f / (1.0f + __expf(-x)); }
;     __device__ __forceinline__ void operator()(const f32x4 (&acc)[2][2][4][2], const Unit& u, int wr, int wc, int fr, int fq) const {
;     ...
;                         for (int i = 0; i < 4; ++i) { float xv = acc[ai][bj][m][n][i] + bv[bj][n][i]; float r;
;                             if (type < 2) { const float sg = sigmoidf_(xv); r = -expm1f(-0.606531f * sg); }
.LBB0_1043:
	v_mul_f32_e32 v51, 0xbfb8aa3b, v51
	v_exp_f32_e32 v51, v51
	s_nop 0
	v_add_f32_e32 v51, 1.0, v51
	v_rcp_f32_e32 v59, v51
	s_nop 0
	v_fma_f32 v61, -v51, v59, 1.0
	v_fma_f32 v58, v61, v59, v59
	v_div_fixup_f32 v51, v58, v51, 1.0
	v_mul_f32_e32 v51, 0xbf1b459e, v51
	v_mul_f32_e32 v58, 0x3fb8aa3b, v51
	v_exp_f32_e32 v58, v58
	s_nop 0
	v_sub_f32_e32 v58, 1.0, v58

; __device__ __forceinline__ float sigmoidf_(float x) { return 1.0f / (1.0f + __expf(-x)); }
;     __device__ __forceinline__ void operator()(const f32x4 (&acc)[2][2][4][2], const Unit& u, int wr, int wc, int fr, int fq) const {
;     ...
;                         for (int i = 0; i < 4; ++i) { float xv = acc[ai][bj][m][n][i] + bv[bj][n][i]; float r;
;                             if (type < 2) { const float sg = sigmoidf_(xv); r = -expm1f(-0.606531f * sg); }
.LBB0_1049:
	v_mul_f32_e32 v44, 0xbfb8aa3b, v48
	v_exp_f32_e32 v44, v44
	s_nop 0
	v_add_f32_e32 v44, 1.0, v44
	v_rcp_f32_e32 v49, v44
	s_nop 0
	v_fma_f32 v51, -v44, v49, 1.0
	v_fma_f32 v48, v51, v49, v49
	v_div_fixup_f32 v44, v48, v44, 1.0
	v_mul_f32_e32 v44, 0xbf1b459e, v44
	v_mul_f32_e32 v48, 0x3fb8aa3b, v44
	v_exp_f32_e32 v48, v48
	s_nop 0
	v_sub_f32_e32 v44, 1.0, v48

; __device__ __forceinline__ float sigmoidf_(float x) { return 1.0f / (1.0f + __expf(-x)); }
;     __device__ __forceinline__ void operator()(const f32x4 (&acc)[2][2][4][2], const Unit& u, int wr, int wc, int fr, int fq) const {
;     ...
;                         for (int i = 0; i < 4; ++i) { float xv = acc[ai][bj][m][n][i] + bv[bj][n][i]; float r;
;                             if (type < 2) { const float sg = sigmoidf_(xv); r = -expm1f(-0.606531f * sg); }
.LBB0_1055:
	v_mul_f32_e32 v45, 0xbfb8aa3b, v48
	v_exp_f32_e32 v45, v45
	s_nop 0
	v_add_f32_e32 v45, 1.0, v45
	v_rcp_f32_e32 v49, v45
	s_nop 0
	v_fma_f32 v51, -v45, v49, 1.0
	v_fma_f32 v48, v51, v49, v49
	v_div_fixup_f32 v45, v48, v45, 1.0
	v_mul_f32_e32 v45, 0xbf1b459e, v45
	v_mul_f32_e32 v48, 0x3fb8aa3b, v45
	v_exp_f32_e32 v48, v48
	s_nop 0
	v_sub_f32_e32 v45, 1.0, v48

; __device__ __forceinline__ float sigmoidf_(float x) { return 1.0f / (1.0f + __expf(-x)); }
;     __device__ __forceinline__ void operator()(const f32x4 (&acc)[2][2][4][2], const Unit& u, int wr, int wc, int fr, int fq) const {
;     ...
;                         for (int i = 0; i < 4; ++i) { float xv = acc[ai][bj][m][n][i] + bv[bj][n][i]; float r;
;                             if (type < 2) { const float sg = sigmoidf_(xv); r = -expm1f(-0.606531f * sg); }
.LBB0_1061:
	v_mul_f32_e32 v46, 0xbfb8aa3b, v48
	v_exp_f32_e32 v46, v46
	s_nop 0
	v_add_f32_e32 v46, 1.0, v46
	v_rcp_f32_e32 v49, v46
	s_nop 0
	v_fma_f32 v51, -v46, v49, 1.0
	v_fma_f32 v48, v51, v49, v49
	v_div_fixup_f32 v46, v48, v46, 1.0
	v_mul_f32_e32 v46, 0xbf1b459e, v46
	v_mul_f32_e32 v48, 0x3fb8aa3b, v46
	v_exp_f32_e32 v48, v48
	s_nop 0
	v_sub_f32_e32 v46, 1.0, v48

; __device__ __forceinline__ float sigmoidf_(float x) { return 1.0f / (1.0f + __expf(-x)); }
;     __device__ __forceinline__ void operator()(const f32x4 (&acc)[2][2][4][2], const Unit& u, int wr, int wc, int fr, int fq) const {
;     ...
;                         for (int i = 0; i < 4; ++i) { float xv = acc[ai][bj][m][n][i] + bv[bj][n][i]; float r;
;                             if (type < 2) { const float sg = sigmoidf_(xv); r = -expm1f(-0.606531f * sg); }
.LBB0_1067:
	v_mul_f32_e32 v47, 0xbfb8aa3b, v48
	v_exp_f32_e32 v47, v47
	s_nop 0
	v_add_f32_e32 v47, 1.0, v47
	v_rcp_f32_e32 v49, v47
	s_nop 0
	v_fma_f32 v51, -v47, v49, 1.0
	v_fma_f32 v48, v51, v49, v49
	v_div_fixup_f32 v47, v48, v47, 1.0
	v_mul_f32_e32 v47, 0xbf1b459e, v47
	v_mul_f32_e32 v48, 0x3fb8aa3b, v47
	v_exp_f32_e32 v48, v48
	s_nop 0
	v_sub_f32_e32 v47, 1.0, v48

; __device__ __forceinline__ float sigmoidf_(float x) { return 1.0f / (1.0f + __expf(-x)); }
;     __device__ __forceinline__ void operator()(const f32x4 (&acc)[2][2][4][2], const Unit& u, int wr, int wc, int fr, int fq) const {
;     ...
;                         for (int i = 0; i < 4; ++i) { float xv = acc[ai][bj][m][n][i] + bv[bj][n][i]; float r;
;                             if (type < 2) { const float sg = sigmoidf_(xv); r = -expm1f(-0.606531f * sg); }
.LBB0_1073:
	v_mul_f32_e32 v40, 0xbfb8aa3b, v40
	v_exp_f32_e32 v40, v40
	s_nop 0
	v_add_f32_e32 v40, 1.0, v40
	v_rcp_f32_e32 v49, v40
	s_nop 0
	v_fma_f32 v51, -v40, v49, 1.0
	v_fma_f32 v48, v51, v49, v49
	v_div_fixup_f32 v40, v48, v40, 1.0
	v_mul_f32_e32 v40, 0xbf1b459e, v40
	v_mul_f32_e32 v48, 0x3fb8aa3b, v40
	v_exp_f32_e32 v48, v48
	s_nop 0
	v_sub_f32_e32 v48, 1.0, v48

; __device__ __forceinline__ float sigmoidf_(float x) { return 1.0f / (1.0f + __expf(-x)); }
;     __device__ __forceinline__ void operator()(const f32x4 (&acc)[2][2][4][2], const Unit& u, int wr, int wc, int fr, int fq) const {
;     ...
;                         for (int i = 0; i < 4; ++i) { float xv = acc[ai][bj][m][n][i] + bv[bj][n][i]; float r;
;                             if (type < 2) { const float sg = sigmoidf_(xv); r = -expm1f(-0.606531f * sg); }
.LBB0_1079:
	v_mul_f32_e32 v40, 0xbfb8aa3b, v40
	v_exp_f32_e32 v40, v40
	s_nop 0
	v_add_f32_e32 v40, 1.0, v40
	v_rcp_f32_e32 v49, v40
	s_nop 0
	v_fma_f32 v51, -v40, v49, 1.0
	v_fma_f32 v41, v51, v49, v49
	v_div_fixup_f32 v40, v41, v40, 1.0
	v_mul_f32_e32 v40, 0xbf1b459e, v40
	v_mul_f32_e32 v41, 0x3fb8aa3b, v40
	v_exp_f32_e32 v41, v41
	s_nop 0
	v_sub_f32_e32 v49, 1.0, v41

; __device__ __forceinline__ float sigmoidf_(float x) { return 1.0f / (1.0f + __expf(-x)); }
;     __device__ __forceinline__ void operator()(const f32x4 (&acc)[2][2][4][2], const Unit& u, int wr, int wc, int fr, int fq) const {
;     ...
;                         for (int i = 0; i < 4; ++i) { float xv = acc[ai][bj][m][n][i] + bv[bj][n][i]; float r;
;                             if (type < 2) { const float sg = sigmoidf_(xv); r = -expm1f(-0.606531f * sg); }
.LBB0_1085:
	v_mul_f32_e32 v40, 0xbfb8aa3b, v40
	v_exp_f32_e32 v40, v40
	s_nop 0
	v_add_f32_e32 v40, 1.0, v40
	v_rcp_f32_e32 v42, v40
	s_nop 0
	v_fma_f32 v51, -v40, v42, 1.0
	v_fma_f32 v41, v51, v42, v42
	v_div_fixup_f32 v40, v41, v40, 1.0
	v_mul_f32_e32 v40, 0xbf1b459e, v40
	v_mul_f32_e32 v41, 0x3fb8aa3b, v40
	v_exp_f32_e32 v41, v41
	s_nop 0
	v_sub_f32_e32 v42, 1.0, v41

; __device__ __forceinline__ float sigmoidf_(float x) { return 1.0f / (1.0f + __expf(-x)); }
;     __device__ __forceinline__ void operator()(const f32x4 (&acc)[2][2][4][2], const Unit& u, int wr, int wc, int fr, int fq) const {
;     ...
;                         for (int i = 0; i < 4; ++i) { float xv = acc[ai][bj][m][n][i] + bv[bj][n][i]; float r;
;                             if (type < 2) { const float sg = sigmoidf_(xv); r = -expm1f(-0.606531f * sg); }
.LBB0_1091:
	v_mul_f32_e32 v40, 0xbfb8aa3b, v40
	v_exp_f32_e32 v40, v40
	s_nop 0
	v_add_f32_e32 v40, 1.0, v40
	v_rcp_f32_e32 v43, v40
	s_nop 0
	v_fma_f32 v51, -v40, v43, 1.0
	v_fma_f32 v41, v51, v43, v43
	v_div_fixup_f32 v40, v41, v40, 1.0
	v_mul_f32_e32 v40, 0xbf1b459e, v40
	v_mul_f32_e32 v41, 0x3fb8aa3b, v40
	v_exp_f32_e32 v41, v41
	s_nop 0
	v_sub_f32_e32 v43, 1.0, v41

; __device__ __forceinline__ float sigmoidf_(float x) { return 1.0f / (1.0f + __expf(-x)); }
;     __device__ __forceinline__ void operator()(const f32x4 (&acc)[2][2][4][2], const Unit& u, int wr, int wc, int fr, int fq) const {
;     ...
;                         for (int i = 0; i < 4; ++i) { float xv = acc[ai][bj][m][n][i] + bv[bj][n][i]; float r;
;                             if (type < 2) { const float sg = sigmoidf_(xv); r = -expm1f(-0.606531f * sg); }
.LBB0_1097:
	v_mul_f32_e32 v36, 0xbfb8aa3b, v42
	v_exp_f32_e32 v36, v36
	s_nop 0
	v_add_f32_e32 v36, 1.0, v36
	v_rcp_f32_e32 v43, v36
	s_nop 0
	v_fma_f32 v45, -v36, v43, 1.0
	v_fma_f32 v42, v45, v43, v43
	v_div_fixup_f32 v36, v42, v36, 1.0
	v_mul_f32_e32 v36, 0xbf1b459e, v36
	v_mul_f32_e32 v42, 0x3fb8aa3b, v36
	v_exp_f32_e32 v42, v42
	s_nop 0
	v_sub_f32_e32 v36, 1.0, v42

; __device__ __forceinline__ float sigmoidf_(float x) { return 1.0f / (1.0f + __expf(-x)); }
;     __device__ __forceinline__ void operator()(const f32x4 (&acc)[2][2][4][2], const Unit& u, int wr, int wc, int fr, int fq) const {
;     ...
;                         for (int i = 0; i < 4; ++i) { float xv = acc[ai][bj][m][n][i] + bv[bj][n][i]; float r;
;                             if (type < 2) { const float sg = sigmoidf_(xv); r = -expm1f(-0.606531f * sg); }
.LBB0_1103:
	v_mul_f32_e32 v37, 0xbfb8aa3b, v42
	v_exp_f32_e32 v37, v37
	s_nop 0
	v_add_f32_e32 v37, 1.0, v37
	v_rcp_f32_e32 v43, v37
	s_nop 0
	v_fma_f32 v45, -v37, v43, 1.0
	v_fma_f32 v42, v45, v43, v43
	v_div_fixup_f32 v37, v42, v37, 1.0
	v_mul_f32_e32 v37, 0xbf1b459e, v37
	v_mul_f32_e32 v42, 0x3fb8aa3b, v37
	v_exp_f32_e32 v42, v42
	s_nop 0
	v_sub_f32_e32 v37, 1.0, v42

; __device__ __forceinline__ float sigmoidf_(float x) { return 1.0f / (1.0f + __expf(-x)); }
;     __device__ __forceinline__ void operator()(const f32x4 (&acc)[2][2][4][2], const Unit& u, int wr, int wc, int fr, int fq) const {
;     ...
;                         for (int i = 0; i < 4; ++i) { float xv = acc[ai][bj][m][n][i] + bv[bj][n][i]; float r;
;                             if (type < 2) { const float sg = sigmoidf_(xv); r = -expm1f(-0.606531f * sg); }
.LBB0_1109:
	v_mul_f32_e32 v38, 0xbfb8aa3b, v42
	v_exp_f32_e32 v38, v38
	s_nop 0
	v_add_f32_e32 v38, 1.0, v38
	v_rcp_f32_e32 v43, v38
	s_nop 0
	v_fma_f32 v45, -v38, v43, 1.0
	v_fma_f32 v42, v45, v43, v43
	v_div_fixup_f32 v38, v42, v38, 1.0
	v_mul_f32_e32 v38, 0xbf1b459e, v38
	v_mul_f32_e32 v42, 0x3fb8aa3b, v38
	v_exp_f32_e32 v42, v42
	s_nop 0
	v_sub_f32_e32 v38, 1.0, v42

; __device__ __forceinline__ float sigmoidf_(float x) { return 1.0f / (1.0f + __expf(-x)); }
;     __device__ __forceinline__ void operator()(const f32x4 (&acc)[2][2][4][2], const Unit& u, int wr, int wc, int fr, int fq) const {
;     ...
;                         for (int i = 0; i < 4; ++i) { float xv = acc[ai][bj][m][n][i] + bv[bj][n][i]; float r;
;                             if (type < 2) { const float sg = sigmoidf_(xv); r = -expm1f(-0.606531f * sg); }
.LBB0_1115:
	v_mul_f32_e32 v39, 0xbfb8aa3b, v42
	v_exp_f32_e32 v39, v39
	s_nop 0
	v_add_f32_e32 v39, 1.0, v39
	v_rcp_f32_e32 v43, v39
	s_nop 0
	v_fma_f32 v45, -v39, v43, 1.0
	v_fma_f32 v42, v45, v43, v43
	v_div_fixup_f32 v39, v42, v39, 1.0
	v_mul_f32_e32 v39, 0xbf1b459e, v39
	v_mul_f32_e32 v42, 0x3fb8aa3b, v39
	v_exp_f32_e32 v42, v42
	s_nop 0
	v_sub_f32_e32 v39, 1.0, v42

; __device__ __forceinline__ float sigmoidf_(float x) { return 1.0f / (1.0f + __expf(-x)); }
;     __device__ __forceinline__ void operator()(const f32x4 (&acc)[2][2][4][2], const Unit& u, int wr, int wc, int fr, int fq) const {
;     ...
;                         for (int i = 0; i < 4; ++i) { float xv = acc[ai][bj][m][n][i] + bv[bj][n][i]; float r;
;                             if (type < 2) { const float sg = sigmoidf_(xv); r = -expm1f(-0.606531f * sg); }
.LBB0_1121:
	v_mul_f32_e32 v24, 0xbfb8aa3b, v42
	v_exp_f32_e32 v24, v24
	s_nop 0
	v_add_f32_e32 v24, 1.0, v24
	v_rcp_f32_e32 v43, v24
	s_nop 0
	v_fma_f32 v45, -v24, v43, 1.0
	v_fma_f32 v42, v45, v43, v43
	v_div_fixup_f32 v24, v42, v24, 1.0
	v_mul_f32_e32 v24, 0xbf1b459e, v24
	v_mul_f32_e32 v42, 0x3fb8aa3b, v24
	v_exp_f32_e32 v42, v42
	s_nop 0
	v_sub_f32_e32 v24, 1.0, v42

; __device__ __forceinline__ float sigmoidf_(float x) { return 1.0f / (1.0f + __expf(-x)); }
;     __device__ __forceinline__ void operator()(const f32x4 (&acc)[2][2][4][2], const Unit& u, int wr, int wc, int fr, int fq) const {
;     ...
;                         for (int i = 0; i < 4; ++i) { float xv = acc[ai][bj][m][n][i] + bv[bj][n][i]; float r;
;                             if (type < 2) { const float sg = sigmoidf_(xv); r = -expm1f(-0.606531f * sg); }
.LBB0_1127:
	v_mul_f32_e32 v25, 0xbfb8aa3b, v42
	v_exp_f32_e32 v25, v25
	s_nop 0
	v_add_f32_e32 v25, 1.0, v25
	v_rcp_f32_e32 v43, v25
	s_nop 0
	v_fma_f32 v45, -v25, v43, 1.0
	v_fma_f32 v42, v45, v43, v43
	v_div_fixup_f32 v25, v42, v25, 1.0
	v_mul_f32_e32 v25, 0xbf1b459e, v25
	v_mul_f32_e32 v42, 0x3fb8aa3b, v25
	v_exp_f32_e32 v42, v42
	s_nop 0
	v_sub_f32_e32 v25, 1.0, v42

; __device__ __forceinline__ float sigmoidf_(float x) { return 1.0f / (1.0f + __expf(-x)); }
;     __device__ __forceinline__ void operator()(const f32x4 (&acc)[2][2][4][2], const Unit& u, int wr, int wc, int fr, int fq) const {
;     ...
;                         for (int i = 0; i < 4; ++i) { float xv = acc[ai][bj][m][n][i] + bv[bj][n][i]; float r;
;                             if (type < 2) { const float sg = sigmoidf_(xv); r = -expm1f(-0.606531f * sg); }
.LBB0_1133:
	v_mul_f32_e32 v26, 0xbfb8aa3b, v42
	v_exp_f32_e32 v26, v26
	s_nop 0
	v_add_f32_e32 v26, 1.0, v26
	v_rcp_f32_e32 v43, v26
	s_nop 0
	v_fma_f32 v45, -v26, v43, 1.0
	v_fma_f32 v42, v45, v43, v43
	v_div_fixup_f32 v26, v42, v26, 1.0
	v_mul_f32_e32 v26, 0xbf1b459e, v26
	v_mul_f32_e32 v42, 0x3fb8aa3b, v26
	v_exp_f32_e32 v42, v42
	s_nop 0
	v_sub_f32_e32 v26, 1.0, v42

; __device__ __forceinline__ float sigmoidf_(float x) { return 1.0f / (1.0f + __expf(-x)); }
;     __device__ __forceinline__ void operator()(const f32x4 (&acc)[2][2][4][2], const Unit& u, int wr, int wc, int fr, int fq) const {
;     ...
;                         for (int i = 0; i < 4; ++i) { float xv = acc[ai][bj][m][n][i] + bv[bj][n][i]; float r;
;                             if (type < 2) { const float sg = sigmoidf_(xv); r = -expm1f(-0.606531f * sg); }
.LBB0_1139:
	v_mul_f32_e32 v27, 0xbfb8aa3b, v27
	v_exp_f32_e32 v27, v27
	s_nop 0
	v_add_f32_e32 v27, 1.0, v27
	v_rcp_f32_e32 v43, v27
	s_nop 0
	v_fma_f32 v45, -v27, v43, 1.0
	v_fma_f32 v42, v45, v43, v43
	v_div_fixup_f32 v27, v42, v27, 1.0
	v_mul_f32_e32 v27, 0xbf1b459e, v27
	v_mul_f32_e32 v42, 0x3fb8aa3b, v27
	v_exp_f32_e32 v42, v42
	s_nop 0
	v_sub_f32_e32 v42, 1.0, v42

; __device__ __forceinline__ float sigmoidf_(float x) { return 1.0f / (1.0f + __expf(-x)); }
;     __device__ __forceinline__ void operator()(const f32x4 (&acc)[2][2][4][2], const Unit& u, int wr, int wc, int fr, int fq) const {
;     ...
;                         for (int i = 0; i < 4; ++i) { float xv = acc[ai][bj][m][n][i] + bv[bj][n][i]; float r;
;                             if (type < 2) { const float sg = sigmoidf_(xv); r = -expm1f(-0.606531f * sg); }
.LBB0_1145:
	v_mul_f32_e32 v16, 0xbfb8aa3b, v24
	v_exp_f32_e32 v16, v16
	s_nop 0
	v_add_f32_e32 v16, 1.0, v16
	v_rcp_f32_e32 v25, v16
	s_nop 0
	v_fma_f32 v27, -v16, v25, 1.0
	v_fma_f32 v24, v27, v25, v25
	v_div_fixup_f32 v16, v24, v16, 1.0
	v_mul_f32_e32 v16, 0xbf1b459e, v16
	v_mul_f32_e32 v24, 0x3fb8aa3b, v16
	v_exp_f32_e32 v24, v24
	s_nop 0
	v_sub_f32_e32 v16, 1.0, v24

; __device__ __forceinline__ float sigmoidf_(float x) { return 1.0f / (1.0f + __expf(-x)); }
;     __device__ __forceinline__ void operator()(const f32x4 (&acc)[2][2][4][2], const Unit& u, int wr, int wc, int fr, int fq) const {
;     ...
;                         for (int i = 0; i < 4; ++i) { float xv = acc[ai][bj][m][n][i] + bv[bj][n][i]; float r;
;                             if (type < 2) { const float sg = sigmoidf_(xv); r = -expm1f(-0.606531f * sg); }
.LBB0_1151:
	v_mul_f32_e32 v17, 0xbfb8aa3b, v24
	v_exp_f32_e32 v17, v17
	s_nop 0
	v_add_f32_e32 v17, 1.0, v17
	v_rcp_f32_e32 v25, v17
	s_nop 0
	v_fma_f32 v27, -v17, v25, 1.0
	v_fma_f32 v24, v27, v25, v25
	v_div_fixup_f32 v17, v24, v17, 1.0
	v_mul_f32_e32 v17, 0xbf1b459e, v17
	v_mul_f32_e32 v24, 0x3fb8aa3b, v17
	v_exp_f32_e32 v24, v24
	s_nop 0
	v_sub_f32_e32 v17, 1.0, v24

; __device__ __forceinline__ float sigmoidf_(float x) { return 1.0f / (1.0f + __expf(-x)); }
;     __device__ __forceinline__ void operator()(const f32x4 (&acc)[2][2][4][2], const Unit& u, int wr, int wc, int fr, int fq) const {
;     ...
;                         for (int i = 0; i < 4; ++i) { float xv = acc[ai][bj][m][n][i] + bv[bj][n][i]; float r;
;                             if (type < 2) { const float sg = sigmoidf_(xv); r = -expm1f(-0.606531f * sg); }
.LBB0_1157:
	v_mul_f32_e32 v18, 0xbfb8aa3b, v24
	v_exp_f32_e32 v18, v18
	s_nop 0
	v_add_f32_e32 v18, 1.0, v18
	v_rcp_f32_e32 v25, v18
	s_nop 0
	v_fma_f32 v27, -v18, v25, 1.0
	v_fma_f32 v24, v27, v25, v25
	v_div_fixup_f32 v18, v24, v18, 1.0
	v_mul_f32_e32 v18, 0xbf1b459e, v18
	v_mul_f32_e32 v24, 0x3fb8aa3b, v18
	v_exp_f32_e32 v24, v24
	s_nop 0
	v_sub_f32_e32 v18, 1.0, v24

; __device__ __forceinline__ float sigmoidf_(float x) { return 1.0f / (1.0f + __expf(-x)); }
;     __device__ __forceinline__ void operator()(const f32x4 (&acc)[2][2][4][2], const Unit& u, int wr, int wc, int fr, int fq) const {
;     ...
;                         for (int i = 0; i < 4; ++i) { float xv = acc[ai][bj][m][n][i] + bv[bj][n][i]; float r;
;                             if (type < 2) { const float sg = sigmoidf_(xv); r = -expm1f(-0.606531f * sg); }
.LBB0_1163:
	v_mul_f32_e32 v19, 0xbfb8aa3b, v24
	v_exp_f32_e32 v19, v19
	s_nop 0
	v_add_f32_e32 v19, 1.0, v19
	v_rcp_f32_e32 v25, v19
	s_nop 0
	v_fma_f32 v27, -v19, v25, 1.0
	v_fma_f32 v24, v27, v25, v25
	v_div_fixup_f32 v19, v24, v19, 1.0
	v_mul_f32_e32 v19, 0xbf1b459e, v19
	v_mul_f32_e32 v24, 0x3fb8aa3b, v19
	v_exp_f32_e32 v24, v24
	s_nop 0
	v_sub_f32_e32 v19, 1.0, v24

; __device__ __forceinline__ float sigmoidf_(float x) { return 1.0f / (1.0f + __expf(-x)); }
;     __device__ __forceinline__ void operator()(const f32x4 (&acc)[2][2][4][2], const Unit& u, int wr, int wc, int fr, int fq) const {
;     ...
;                         for (int i = 0; i < 4; ++i) { float xv = acc[ai][bj][m][n][i] + bv[bj][n][i]; float r;
;                             if (type < 2) { const float sg = sigmoidf_(xv); r = -expm1f(-0.606531f * sg); }
.LBB0_1169:
	v_mul_f32_e32 v8, 0xbfb8aa3b, v8
	v_exp_f32_e32 v8, v8
	s_nop 0
	v_add_f32_e32 v8, 1.0, v8
	v_rcp_f32_e32 v25, v8
	s_nop 0
	v_fma_f32 v27, -v8, v25, 1.0
	v_fma_f32 v24, v27, v25, v25
	v_div_fixup_f32 v8, v24, v8, 1.0
	v_mul_f32_e32 v8, 0xbf1b459e, v8
	v_mul_f32_e32 v24, 0x3fb8aa3b, v8
	v_exp_f32_e32 v24, v24
	s_nop 0
	v_sub_f32_e32 v24, 1.0, v24

; __device__ __forceinline__ float sigmoidf_(float x) { return 1.0f / (1.0f + __expf(-x)); }
;     __device__ __forceinline__ void operator()(const f32x4 (&acc)[2][2][4][2], const Unit& u, int wr, int wc, int fr, int fq) const {
;     ...
;                         for (int i = 0; i < 4; ++i) { float xv = acc[ai][bj][m][n][i] + bv[bj][n][i]; float r;
;                             if (type < 2) { const float sg = sigmoidf_(xv); r = -expm1f(-0.606531f * sg); }
.LBB0_1175:
	v_mul_f32_e32 v8, 0xbfb8aa3b, v8
	v_exp_f32_e32 v8, v8
	s_nop 0
	v_add_f32_e32 v8, 1.0, v8
	v_rcp_f32_e32 v25, v8
	s_nop 0
	v_fma_f32 v27, -v8, v25, 1.0
	v_fma_f32 v9, v27, v25, v25
	v_div_fixup_f32 v8, v9, v8, 1.0
	v_mul_f32_e32 v8, 0xbf1b459e, v8
	v_mul_f32_e32 v9, 0x3fb8aa3b, v8
	v_exp_f32_e32 v9, v9
	s_nop 0
	v_sub_f32_e32 v25, 1.0, v9

; __device__ __forceinline__ float sigmoidf_(float x) { return 1.0f / (1.0f + __expf(-x)); }
;     __device__ __forceinline__ void operator()(const f32x4 (&acc)[2][2][4][2], const Unit& u, int wr, int wc, int fr, int fq) const {
;     ...
;                         for (int i = 0; i < 4; ++i) { float xv = acc[ai][bj][m][n][i] + bv[bj][n][i]; float r;
;                             if (type < 2) { const float sg = sigmoidf_(xv); r = -expm1f(-0.606531f * sg); }
.LBB0_1181:
	v_mul_f32_e32 v8, 0xbfb8aa3b, v8
	v_exp_f32_e32 v8, v8
	s_nop 0
	v_add_f32_e32 v8, 1.0, v8
	v_rcp_f32_e32 v10, v8
	s_nop 0
	v_fma_f32 v27, -v8, v10, 1.0
	v_fma_f32 v9, v27, v10, v10
	v_div_fixup_f32 v8, v9, v8, 1.0
	v_mul_f32_e32 v8, 0xbf1b459e, v8
	v_mul_f32_e32 v9, 0x3fb8aa3b, v8
	v_exp_f32_e32 v9, v9
	s_nop 0
	v_sub_f32_e32 v10, 1.0, v9

; __device__ __forceinline__ float sigmoidf_(float x) { return 1.0f / (1.0f + __expf(-x)); }
;     __device__ __forceinline__ void operator()(const f32x4 (&acc)[2][2][4][2], const Unit& u, int wr, int wc, int fr, int fq) const {
;     ...
;                         for (int i = 0; i < 4; ++i) { float xv = acc[ai][bj][m][n][i] + bv[bj][n][i]; float r;
;                             if (type < 2) { const float sg = sigmoidf_(xv); r = -expm1f(-0.606531f * sg); }
.LBB0_1187:
	v_mul_f32_e32 v8, 0xbfb8aa3b, v8
	v_exp_f32_e32 v8, v8
	s_nop 0
	v_add_f32_e32 v8, 1.0, v8
	v_rcp_f32_e32 v11, v8
	s_nop 0
	v_fma_f32 v27, -v8, v11, 1.0
	v_fma_f32 v9, v27, v11, v11
	v_div_fixup_f32 v8, v9, v8, 1.0
	v_mul_f32_e32 v8, 0xbf1b459e, v8
	v_mul_f32_e32 v9, 0x3fb8aa3b, v8
	v_exp_f32_e32 v9, v9
	s_nop 0
	v_sub_f32_e32 v11, 1.0, v9

; __device__ __forceinline__ float sigmoidf_(float x) { return 1.0f / (1.0f + __expf(-x)); }
;     __device__ __forceinline__ void operator()(const f32x4 (&acc)[2][2][4][2], const Unit& u, int wr, int wc, int fr, int fq) const {
;     ...
;                         for (int i = 0; i < 4; ++i) { float xv = acc[ai][bj][m][n][i] + bv[bj][n][i]; float r;
;                             if (type < 2) { const float sg = sigmoidf_(xv); r = -expm1f(-0.606531f * sg); }
.LBB0_1193:
	v_mul_f32_e32 v4, 0xbfb8aa3b, v10
	v_exp_f32_e32 v4, v4
	s_nop 0
	v_add_f32_e32 v4, 1.0, v4
	v_rcp_f32_e32 v11, v4
	s_nop 0
	v_fma_f32 v17, -v4, v11, 1.0
	v_fma_f32 v10, v17, v11, v11
	v_div_fixup_f32 v4, v10, v4, 1.0
	v_mul_f32_e32 v4, 0xbf1b459e, v4
	v_mul_f32_e32 v10, 0x3fb8aa3b, v4
	v_exp_f32_e32 v10, v10
	s_nop 0
	v_sub_f32_e32 v4, 1.0, v10

; __device__ __forceinline__ float sigmoidf_(float x) { return 1.0f / (1.0f + __expf(-x)); }
;     __device__ __forceinline__ void operator()(const f32x4 (&acc)[2][2][4][2], const Unit& u, int wr, int wc, int fr, int fq) const {
;     ...
;                         for (int i = 0; i < 4; ++i) { float xv = acc[ai][bj][m][n][i] + bv[bj][n][i]; float r;
;                             if (type < 2) { const float sg = sigmoidf_(xv); r = -expm1f(-0.606531f * sg); }
.LBB0_1199:
	v_mul_f32_e32 v5, 0xbfb8aa3b, v10
	v_exp_f32_e32 v5, v5
	s_nop 0
	v_add_f32_e32 v5, 1.0, v5
	v_rcp_f32_e32 v11, v5
	s_nop 0
	v_fma_f32 v17, -v5, v11, 1.0
	v_fma_f32 v10, v17, v11, v11
	v_div_fixup_f32 v5, v10, v5, 1.0
	v_mul_f32_e32 v5, 0xbf1b459e, v5
	v_mul_f32_e32 v10, 0x3fb8aa3b, v5
	v_exp_f32_e32 v10, v10
	s_nop 0
	v_sub_f32_e32 v5, 1.0, v10

; __device__ __forceinline__ float sigmoidf_(float x) { return 1.0f / (1.0f + __expf(-x)); }
;     __device__ __forceinline__ void operator()(const f32x4 (&acc)[2][2][4][2], const Unit& u, int wr, int wc, int fr, int fq) const {
;     ...
;                         for (int i = 0; i < 4; ++i) { float xv = acc[ai][bj][m][n][i] + bv[bj][n][i]; float r;
;                             if (type < 2) { const float sg = sigmoidf_(xv); r = -expm1f(-0.606531f * sg); }
.LBB0_1205:
	v_mul_f32_e32 v6, 0xbfb8aa3b, v10
	v_exp_f32_e32 v6, v6
	s_nop 0
	v_add_f32_e32 v6, 1.0, v6
	v_rcp_f32_e32 v11, v6
	s_nop 0
	v_fma_f32 v17, -v6, v11, 1.0
	v_fma_f32 v10, v17, v11, v11
	v_div_fixup_f32 v6, v10, v6, 1.0
	v_mul_f32_e32 v6, 0xbf1b459e, v6
	v_mul_f32_e32 v10, 0x3fb8aa3b, v6
	v_exp_f32_e32 v10, v10
	s_nop 0
	v_sub_f32_e32 v6, 1.0, v10

; __device__ __forceinline__ float sigmoidf_(float x) { return 1.0f / (1.0f + __expf(-x)); }
;     __device__ __forceinline__ void operator()(const f32x4 (&acc)[2][2][4][2], const Unit& u, int wr, int wc, int fr, int fq) const {
;     ...
;                         for (int i = 0; i < 4; ++i) { float xv = acc[ai][bj][m][n][i] + bv[bj][n][i]; float r;
;                             if (type < 2) { const float sg = sigmoidf_(xv); r = -expm1f(-0.606531f * sg); }
.LBB0_1211:
	v_mul_f32_e32 v7, 0xbfb8aa3b, v10
	v_exp_f32_e32 v7, v7
	s_nop 0
	v_add_f32_e32 v7, 1.0, v7
	v_rcp_f32_e32 v11, v7
	s_nop 0
	v_fma_f32 v17, -v7, v11, 1.0
	v_fma_f32 v10, v17, v11, v11
	v_div_fixup_f32 v7, v10, v7, 1.0
	v_mul_f32_e32 v7, 0xbf1b459e, v7
	v_mul_f32_e32 v10, 0x3fb8aa3b, v7
	v_exp_f32_e32 v10, v10
	s_nop 0
	v_sub_f32_e32 v7, 1.0, v10

; __device__ __forceinline__ float sigmoidf_(float x) { return 1.0f / (1.0f + __expf(-x)); }
;     __device__ __forceinline__ void operator()(const f32x4 (&acc)[2][2][4][2], const Unit& u, int wr, int wc, int fr, int fq) const {
;     ...
;                         for (int i = 0; i < 4; ++i) { float xv = acc[ai][bj][m][n][i] + bv[bj][n][i]; float r;
;                             if (type < 2) { const float sg = sigmoidf_(xv); r = -expm1f(-0.606531f * sg); }
.LBB0_1217:
	v_mul_f32_e32 v0, 0xbfb8aa3b, v10
	v_exp_f32_e32 v0, v0
	s_nop 0
	v_add_f32_e32 v0, 1.0, v0
	v_rcp_f32_e32 v11, v0
	s_nop 0
	v_fma_f32 v16, -v0, v11, 1.0
	v_fma_f32 v10, v16, v11, v11
	v_div_fixup_f32 v0, v10, v0, 1.0
	v_mul_f32_e32 v0, 0xbf1b459e, v0
	v_mul_f32_e32 v10, 0x3fb8aa3b, v0
	v_exp_f32_e32 v10, v10
	s_nop 0
	v_sub_f32_e32 v0, 1.0, v10

; __device__ __forceinline__ float sigmoidf_(float x) { return 1.0f / (1.0f + __expf(-x)); }
;     __device__ __forceinline__ void operator()(const f32x4 (&acc)[2][2][4][2], const Unit& u, int wr, int wc, int fr, int fq) const {
;     ...
;                         for (int i = 0; i < 4; ++i) { float xv = acc[ai][bj][m][n][i] + bv[bj][n][i]; float r;
;                             if (type < 2) { const float sg = sigmoidf_(xv); r = -expm1f(-0.606531f * sg); }
.LBB0_1223:
	v_mul_f32_e32 v1, 0xbfb8aa3b, v10
	v_exp_f32_e32 v1, v1
	s_nop 0
	v_add_f32_e32 v1, 1.0, v1
	v_rcp_f32_e32 v11, v1
	s_nop 0
	v_fma_f32 v13, -v1, v11, 1.0
	v_fma_f32 v10, v13, v11, v11
	v_div_fixup_f32 v1, v10, v1, 1.0
	v_mul_f32_e32 v1, 0xbf1b459e, v1
	v_mul_f32_e32 v10, 0x3fb8aa3b, v1
	v_exp_f32_e32 v10, v10
	s_nop 0
	v_sub_f32_e32 v1, 1.0, v10

; __device__ __forceinline__ float sigmoidf_(float x) { return 1.0f / (1.0f + __expf(-x)); }
;     __device__ __forceinline__ void operator()(const f32x4 (&acc)[2][2][4][2], const Unit& u, int wr, int wc, int fr, int fq) const {
;     ...
;                         for (int i = 0; i < 4; ++i) { float xv = acc[ai][bj][m][n][i] + bv[bj][n][i]; float r;
;                             if (type < 2) { const float sg = sigmoidf_(xv); r = -expm1f(-0.606531f * sg); }
.LBB0_1229:
	v_mul_f32_e32 v2, 0xbfb8aa3b, v10
	v_exp_f32_e32 v2, v2
	s_nop 0
	v_add_f32_e32 v2, 1.0, v2
	v_rcp_f32_e32 v11, v2
	s_nop 0
	v_fma_f32 v13, -v2, v11, 1.0
	v_fma_f32 v10, v13, v11, v11
	v_div_fixup_f32 v2, v10, v2, 1.0
	v_mul_f32_e32 v2, 0xbf1b459e, v2
	v_mul_f32_e32 v10, 0x3fb8aa3b, v2
	v_exp_f32_e32 v10, v10
	s_nop 0
	v_sub_f32_e32 v2, 1.0, v10

; __device__ __forceinline__ float sigmoidf_(float x) { return 1.0f / (1.0f + __expf(-x)); }
;     __device__ __forceinline__ void operator()(const f32x4 (&acc)[2][2][4][2], const Unit& u, int wr, int wc, int fr, int fq) const {
;     ...
;                         for (int i = 0; i < 4; ++i) { float xv = acc[ai][bj][m][n][i] + bv[bj][n][i]; float r;
;                             if (type < 2) { const float sg = sigmoidf_(xv); r = -expm1f(-0.606531f * sg); }
.LBB0_1235:
	v_mul_f32_e32 v3, 0xbfb8aa3b, v3
	v_exp_f32_e32 v3, v3
	s_nop 0
	v_add_f32_e32 v3, 1.0, v3
	v_rcp_f32_e32 v11, v3
	s_nop 0
	v_fma_f32 v13, -v3, v11, 1.0
	v_fma_f32 v10, v13, v11, v11
	v_div_fixup_f32 v3, v10, v3, 1.0
	v_mul_f32_e32 v3, 0xbf1b459e, v3
	v_mul_f32_e32 v10, 0x3fb8aa3b, v3
	v_exp_f32_e32 v10, v10
	s_nop 0
	v_sub_f32_e32 v10, 1.0, v10
	s_branch .LBB0_443
